# row phases P3/P7/P9/P12: wave_sum xor-1/2/4/8 hops as DPP adds instead of serialized ds_bpermute+wait (same operands per add)
# speedup vs baseline: 1.0062x; 1.0031x over previous
.LBB0_403:
	s_ashr_i32 s1, s0, 31
	s_lshl_b64 s[6:7], s[0:1], 11
	v_lshl_add_u64 v[58:59], v[52:53], 0, s[6:7]
	s_waitcnt lgkmcnt(0)
	global_load_dwordx4 v[32:35], v[58:59], off
	global_load_dwordx4 v[36:39], v[58:59], off offset:1024
	s_add_i32 s4, s0, s83
	s_min_i32 s8, s4, 0xffff
	s_ashr_i32 s9, s8, 31
	s_lshl_b64 s[12:13], s[8:9], 11
	v_lshl_add_u64 v[40:41], v[52:53], 0, s[12:13]
	global_load_dwordx4 v[68:71], v[40:41], off
	global_load_dwordx4 v[48:51], v[40:41], off offset:1024
	s_lshl_b64 s[0:1], s[0:1], 12
	v_lshl_add_u64 v[42:43], v[56:57], 0, s[0:1]
	flat_load_dwordx4 v[72:75], v[42:43]
	flat_load_dwordx4 v[76:79], v[42:43] offset:16
	flat_load_dwordx4 v[82:85], v[42:43] offset:2048
	flat_load_dwordx4 v[96:99], v[42:43] offset:2064
	s_lshl_b64 s[0:1], s[8:9], 12
	v_lshl_add_u64 v[60:61], v[56:57], 0, s[0:1]
	flat_load_dwordx4 v[44:47], v[60:61]
	flat_load_dwordx4 v[40:43], v[60:61] offset:16
	s_cmp_lt_i32 s4, 0x10000
	s_waitcnt vmcnt(0)
	v_and_b32_e32 v81, 0xffff0000, v32
	v_and_b32_e32 v87, 0xffff0000, v33
	v_and_b32_e32 v101, 0xffff0000, v34
	v_and_b32_e32 v103, 0xffff0000, v35
	v_lshlrev_b32_e32 v80, 16, v32
	v_lshlrev_b32_e32 v86, 16, v33
	v_lshlrev_b32_e32 v100, 16, v34
	v_lshlrev_b32_e32 v102, 16, v35
	v_and_b32_e32 v105, 0xffff0000, v36
	v_and_b32_e32 v107, 0xffff0000, v37
	v_mul_f32_e32 v32, v81, v81
	v_mul_f32_e32 v33, v87, v87
	v_mul_f32_e32 v34, v101, v101
	v_mul_f32_e32 v35, v103, v103
	v_lshlrev_b32_e32 v104, 16, v36
	v_lshlrev_b32_e32 v106, 16, v37
	v_and_b32_e32 v109, 0xffff0000, v38
	v_and_b32_e32 v111, 0xffff0000, v39
	v_mul_f32_e32 v36, v105, v105
	v_mul_f32_e32 v37, v107, v107
	v_fmac_f32_e32 v32, v80, v80
	v_fmac_f32_e32 v33, v86, v86
	v_fmac_f32_e32 v34, v100, v100
	v_fmac_f32_e32 v35, v102, v102
	v_lshlrev_b32_e32 v108, 16, v38
	v_lshlrev_b32_e32 v110, 16, v39
	v_mul_f32_e32 v38, v109, v109
	v_mul_f32_e32 v39, v111, v111
	v_fmac_f32_e32 v36, v104, v104
	v_fmac_f32_e32 v37, v106, v106
	v_add_f32_e32 v32, v32, v33
	v_add_f32_e32 v33, v34, v35
	v_fmac_f32_e32 v38, v108, v108
	v_fmac_f32_e32 v39, v110, v110
	v_add_f32_e32 v34, v36, v37
	v_add_f32_e32 v32, v32, v33
	v_add_f32_e32 v35, v38, v39
	v_add_f32_e32 v32, v32, v34
	v_add_f32_e32 v32, v35, v32
	s_nop 1
	v_lshlrev_b32_e32 v66, 16, v71
	v_and_b32_e32 v67, 0xffff0000, v71
	v_lshlrev_b32_e32 v64, 16, v68
	v_and_b32_e32 v65, 0xffff0000, v68
	s_waitcnt lgkmcnt(0)
	v_add_f32_dpp v32, v32, v32 quad_perm:[1,0,3,2] row_mask:0xf bank_mask:0xf
	s_nop 1
	v_lshlrev_b32_e32 v68, 16, v69
	v_and_b32_e32 v69, 0xffff0000, v69
	s_waitcnt lgkmcnt(0)
	v_add_f32_dpp v32, v32, v32 quad_perm:[2,3,0,1] row_mask:0xf bank_mask:0xf
	s_nop 1
	s_waitcnt lgkmcnt(0)
	v_add_f32_dpp v32, v32, v32 row_half_mirror row_mask:0xf bank_mask:0xf
	s_nop 1
	s_waitcnt lgkmcnt(0)
	v_add_f32_dpp v62, v32, v32 row_mirror row_mask:0xf bank_mask:0xf
	ds_bpermute_b32 v63, v92, v62
	flat_load_dwordx4 v[36:39], v[60:61] offset:2048
	flat_load_dwordx4 v[32:35], v[60:61] offset:2064
	s_waitcnt lgkmcnt(0)
	v_add_f32_e32 v60, v62, v63
	ds_bpermute_b32 v61, v93, v60
	v_lshlrev_b32_e32 v62, 16, v70
	v_and_b32_e32 v63, 0xffff0000, v70
	s_waitcnt lgkmcnt(0)
	v_add_f32_e32 v60, v60, v61
	v_fmamk_f32 v60, v60, 0x3a800000, v94
	v_mul_f32_e32 v61, 0x4f800000, v60
	v_cmp_gt_f32_e32 vcc, s10, v60
	s_nop 1
	v_cndmask_b32_e32 v61, v60, v61, vcc
	v_sqrt_f32_e32 v70, v61
	v_lshlrev_b32_e32 v60, 16, v48
	v_add_u32_e32 v71, -1, v70
	v_add_u32_e32 v112, 1, v70
	v_fma_f32 v113, -v71, v70, v61
	v_fma_f32 v114, -v112, v70, v61
	v_cmp_ge_f32_e64 s[0:1], 0, v113
	s_nop 1
	v_cndmask_b32_e64 v70, v70, v71, s[0:1]
	v_cmp_lt_f32_e64 s[0:1], 0, v114
	s_nop 1
	v_cndmask_b32_e64 v70, v70, v112, s[0:1]
	v_mul_f32_e32 v71, 0x37800000, v70
	v_cndmask_b32_e32 v70, v70, v71, vcc
	v_cmp_class_f32_e32 vcc, v61, v95
	s_nop 1
	v_cndmask_b32_e32 v70, v70, v61, vcc
	v_div_scale_f32 v71, s[0:1], v70, v70, 1.0
	v_rcp_f32_e32 v112, v71
	v_and_b32_e32 v61, 0xffff0000, v48
	v_div_scale_f32 v48, vcc, 1.0, v70, 1.0
	v_fma_f32 v113, -v71, v112, 1.0
	v_fmac_f32_e32 v112, v113, v112
	v_mul_f32_e32 v113, v48, v112
	v_fma_f32 v114, -v71, v113, v48
	v_fmac_f32_e32 v113, v114, v112
	v_fma_f32 v48, -v71, v113, v48
	v_div_fmas_f32 v48, v48, v112, v113
	v_div_fixup_f32 v48, v48, v70, 1.0
	v_mul_f32_e32 v48, 0.5, v48
	v_pk_mul_f32 v[80:81], v[48:49], v[80:81] op_sel_hi:[0,1]
	v_pk_mul_f32 v[70:71], v[48:49], v[86:87] op_sel_hi:[0,1]
	v_pk_mul_f32 v[86:87], v[48:49], v[100:101] op_sel_hi:[0,1]
	v_pk_mul_f32 v[100:101], v[48:49], v[102:103] op_sel_hi:[0,1]
	v_pk_mul_f32 v[102:103], v[48:49], v[104:105] op_sel_hi:[0,1]
	v_pk_mul_f32 v[104:105], v[48:49], v[106:107] op_sel_hi:[0,1]
	v_pk_mul_f32 v[106:107], v[48:49], v[108:109] op_sel_hi:[0,1]
	v_pk_mul_f32 v[108:109], v[48:49], v[110:111] op_sel_hi:[0,1]
	v_pk_fma_f32 v[70:71], v[2:3], v[70:71], v[74:75]
	v_pk_fma_f32 v[72:73], v[0:1], v[80:81], v[72:73]
	v_pk_fma_f32 v[74:75], v[6:7], v[100:101], v[78:79]
	v_pk_fma_f32 v[78:79], v[4:5], v[86:87], v[76:77]
	v_pk_fma_f32 v[80:81], v[10:11], v[104:105], v[84:85]
	v_pk_fma_f32 v[84:85], v[14:15], v[108:109], v[98:99]
	v_pk_fma_f32 v[86:87], v[12:13], v[106:107], v[96:97]
	v_pk_mul_f32 v[76:77], v[70:71], v[70:71]
	v_pk_mul_f32 v[96:97], v[72:73], v[72:73]
	v_pk_mul_f32 v[98:99], v[74:75], v[74:75]
	v_pk_mul_f32 v[100:101], v[78:79], v[78:79]
	v_pk_fma_f32 v[82:83], v[8:9], v[102:103], v[82:83]
	v_pk_mov_b32 v[104:105], v[96:97], v[76:77] op_sel:[1,0]
	v_mov_b32_e32 v97, v77
	v_pk_mov_b32 v[76:77], v[100:101], v[98:99] op_sel:[1,0]
	v_mov_b32_e32 v101, v99
	v_mul_f32_e32 v48, v82, v82
	v_mul_f32_e32 v102, v80, v80
	v_pk_add_f32 v[96:97], v[104:105], v[96:97]
	v_pk_add_f32 v[76:77], v[76:77], v[100:101]
	v_pk_fma_f32 v[98:99], v[82:83], v[82:83], v[48:49] op_sel_hi:[1,1,0]
	v_pk_fma_f32 v[102:103], v[80:81], v[80:81], v[102:103] op_sel_hi:[1,1,0]
	v_pk_add_f32 v[96:97], v[96:97], v[96:97] op_sel_hi:[0,1]
	v_pk_add_f32 v[76:77], v[76:77], v[76:77] op_sel_hi:[0,1]
	v_mul_f32_e32 v98, v86, v86
	v_mul_f32_e32 v102, v87, v87
	v_mul_f32_e32 v96, v84, v84
	v_mul_f32_e32 v76, v85, v85
	v_pk_add_f32 v[98:99], v[98:99], v[102:103]
	v_pk_add_f32 v[76:77], v[96:97], v[76:77]
	v_mul_f32_e32 v100, v63, v63
	v_pk_add_f32 v[76:77], v[98:99], v[76:77]
	v_mul_f32_e32 v98, v65, v65
	v_add_f32_e32 v96, v76, v77
	s_nop 1
	v_mul_f32_e32 v99, v69, v69
	v_fmac_f32_e32 v98, v64, v64
	v_fmac_f32_e32 v99, v68, v68
	v_add_f32_e32 v98, v98, v99
	s_waitcnt lgkmcnt(0)
	v_add_f32_dpp v96, v96, v96 quad_perm:[1,0,3,2] row_mask:0xf bank_mask:0xf
	s_nop 1
	v_mul_f32_e32 v101, v67, v67
	v_fmac_f32_e32 v100, v62, v62
	v_fmac_f32_e32 v101, v66, v66
	v_and_b32_e32 v77, 0xffff0000, v49
	s_waitcnt lgkmcnt(0)
	v_add_f32_dpp v96, v96, v96 quad_perm:[2,3,0,1] row_mask:0xf bank_mask:0xf
	s_nop 1
	v_lshlrev_b32_e32 v76, 16, v49
	v_lshlrev_b32_e32 v48, 16, v50
	v_and_b32_e32 v49, 0xffff0000, v50
	v_lshlrev_b32_e32 v50, 16, v51
	s_waitcnt lgkmcnt(0)
	v_add_f32_dpp v96, v96, v96 row_half_mirror row_mask:0xf bank_mask:0xf
	s_nop 1
	v_and_b32_e32 v51, 0xffff0000, v51
	v_mul_f32_e32 v102, v61, v61
	v_fmac_f32_e32 v102, v60, v60
	s_waitcnt lgkmcnt(0)
	v_add_f32_dpp v99, v96, v96 row_mirror row_mask:0xf bank_mask:0xf
	ds_bpermute_b32 v103, v92, v99
	v_add_f32_e32 v96, v100, v101
	v_add_f32_e32 v100, v98, v96
	v_cvt_pk_bf16_f32 v96, v72, v73
	v_cvt_pk_bf16_f32 v97, v70, v71
	s_waitcnt lgkmcnt(0)
	v_add_f32_e32 v101, v99, v103
	ds_bpermute_b32 v103, v93, v101
	v_cvt_pk_bf16_f32 v98, v78, v79
	v_cvt_pk_bf16_f32 v99, v74, v75
	global_store_dwordx4 v[58:59], v[96:99], off
	s_waitcnt lgkmcnt(0)
	s_nop 0
	v_add_f32_e32 v97, v101, v103
	v_fmamk_f32 v97, v97, 0x3a800000, v94
	v_mul_f32_e32 v98, 0x4f800000, v97
	v_cmp_gt_f32_e32 vcc, s10, v97
	v_cvt_pk_bf16_f32 v96, v82, v83
	s_nop 1
	v_cndmask_b32_e32 v101, v97, v98, vcc
	v_sqrt_f32_e32 v103, v101
	v_cvt_pk_bf16_f32 v97, v80, v81
	v_cvt_pk_bf16_f32 v98, v86, v87
	v_cvt_pk_bf16_f32 v99, v84, v85
	global_store_dwordx4 v[58:59], v[96:99], off offset:1024
	v_add_u32_e32 v104, -1, v103
	v_add_u32_e32 v105, 1, v103
	v_fma_f32 v106, -v104, v103, v101
	v_fma_f32 v107, -v105, v103, v101
	v_cmp_ge_f32_e64 s[0:1], 0, v106
	v_mul_f32_e32 v97, v49, v49
	v_mul_f32_e32 v98, v51, v51
	v_cndmask_b32_e64 v103, v103, v104, s[0:1]
	v_cmp_lt_f32_e64 s[0:1], 0, v107
	v_fmac_f32_e32 v97, v48, v48
	v_fmac_f32_e32 v98, v50, v50
	v_cndmask_b32_e64 v103, v103, v105, s[0:1]
	v_mul_f32_e32 v104, 0x37800000, v103
	v_cndmask_b32_e32 v103, v103, v104, vcc
	v_cmp_class_f32_e32 vcc, v101, v95
	v_add_f32_e32 v97, v97, v98
	s_nop 0
	v_cndmask_b32_e32 v101, v103, v101, vcc
	v_div_scale_f32 v103, s[0:1], v101, v101, 1.0
	v_rcp_f32_e32 v104, v103
	v_div_scale_f32 v58, vcc, 1.0, v101, 1.0
	v_fma_f32 v59, -v103, v104, 1.0
	v_fmac_f32_e32 v104, v59, v104
	v_mul_f32_e32 v59, v58, v104
	v_fma_f32 v96, -v103, v59, v58
	v_fmac_f32_e32 v59, v96, v104
	v_mul_f32_e32 v96, v77, v77
	v_fmac_f32_e32 v96, v76, v76
	v_add_f32_e32 v96, v102, v96
	v_add_f32_e32 v96, v100, v96
	v_add_f32_e32 v96, v97, v96
	s_nop 1
	v_fma_f32 v58, -v103, v59, v58
	v_div_fmas_f32 v58, v58, v104, v59
	v_div_fixup_f32 v58, v58, v101, 1.0
	v_pk_mul_f32 v[86:87], v[86:87], v[58:59] op_sel_hi:[1,0]
	s_waitcnt lgkmcnt(0)
	v_add_f32_dpp v59, v96, v96 quad_perm:[1,0,3,2] row_mask:0xf bank_mask:0xf
	s_nop 1
	v_pk_mul_f32 v[84:85], v[84:85], v[58:59] op_sel_hi:[1,0]
	v_pk_mul_f32 v[82:83], v[82:83], v[58:59] op_sel_hi:[1,0]
	v_pk_mul_f32 v[84:85], v[30:31], v[84:85]
	v_pk_mul_f32 v[82:83], v[24:25], v[82:83]
	s_waitcnt lgkmcnt(0)
	v_add_f32_dpp v59, v59, v59 quad_perm:[2,3,0,1] row_mask:0xf bank_mask:0xf
	s_nop 1
	v_pk_mul_f32 v[80:81], v[80:81], v[58:59] op_sel_hi:[1,0]
	v_pk_mul_f32 v[78:79], v[78:79], v[58:59] op_sel_hi:[1,0]
	v_pk_mul_f32 v[86:87], v[28:29], v[86:87]
	v_pk_mul_f32 v[78:79], v[20:21], v[78:79]
	s_waitcnt lgkmcnt(0)
	v_add_f32_dpp v59, v59, v59 row_half_mirror row_mask:0xf bank_mask:0xf
	s_nop 1
	v_pk_mul_f32 v[74:75], v[74:75], v[58:59] op_sel_hi:[1,0]
	v_pk_mul_f32 v[72:73], v[72:73], v[58:59] op_sel_hi:[1,0]
	v_pk_mul_f32 v[74:75], v[22:23], v[74:75]
	v_pk_mul_f32 v[80:81], v[26:27], v[80:81]
	s_waitcnt lgkmcnt(0)
	v_add_f32_dpp v98, v59, v59 row_mirror row_mask:0xf bank_mask:0xf
	ds_bpermute_b32 v99, v92, v98
	v_pk_mul_f32 v[58:59], v[70:71], v[58:59] op_sel_hi:[1,0]
	v_pk_mul_f32 v[70:71], v[16:17], v[72:73]
	v_pk_mul_f32 v[58:59], v[18:19], v[58:59]
	v_cvt_pk_bf16_f32 v70, v70, v71
	s_waitcnt lgkmcnt(0)
	v_add_f32_e32 v98, v98, v99
	ds_bpermute_b32 v99, v93, v98
	v_cvt_pk_bf16_f32 v71, v58, v59
	v_lshl_add_u64 v[96:97], v[54:55], 0, s[6:7]
	v_cvt_pk_bf16_f32 v72, v78, v79
	v_cvt_pk_bf16_f32 v73, v74, v75
	s_waitcnt lgkmcnt(0)
	v_add_f32_e32 v58, v98, v99
	v_fmamk_f32 v58, v58, 0x3a800000, v94
	v_mul_f32_e32 v59, 0x4f800000, v58
	v_cmp_gt_f32_e32 vcc, s10, v58
	global_store_dwordx4 v[96:97], v[70:73], off
	s_mov_b64 s[6:7], -1
	v_cndmask_b32_e32 v58, v58, v59, vcc
	v_sqrt_f32_e32 v59, v58
	v_cvt_pk_bf16_f32 v70, v82, v83
	v_cvt_pk_bf16_f32 v71, v80, v81
	s_nop 0
	v_add_u32_e32 v72, -1, v59
	v_fma_f32 v73, -v72, v59, v58
	v_cmp_ge_f32_e64 s[0:1], 0, v73
	v_add_u32_e32 v73, 1, v59
	s_nop 0
	v_cndmask_b32_e64 v72, v59, v72, s[0:1]
	v_fma_f32 v59, -v73, v59, v58
	v_cmp_lt_f32_e64 s[0:1], 0, v59
	s_nop 1
	v_cndmask_b32_e64 v59, v72, v73, s[0:1]
	v_mul_f32_e32 v72, 0x37800000, v59
	v_cndmask_b32_e32 v59, v59, v72, vcc
	v_cmp_class_f32_e32 vcc, v58, v95
	v_cvt_pk_bf16_f32 v72, v86, v87
	v_cvt_pk_bf16_f32 v73, v84, v85
	global_store_dwordx4 v[96:97], v[70:73], off offset:1024
	s_nop 0
	v_cndmask_b32_e32 v58, v59, v58, vcc
	v_div_scale_f32 v59, s[0:1], v58, v58, 1.0
	v_rcp_f32_e32 v74, v59
	s_cselect_b64 s[0:1], -1, 0
	v_fma_f32 v70, -v59, v74, 1.0
	v_fmac_f32_e32 v74, v70, v74
	v_div_scale_f32 v70, vcc, 1.0, v58, 1.0
	v_mul_f32_e32 v71, v70, v74
	v_fma_f32 v72, -v59, v71, v70
	v_fmac_f32_e32 v71, v72, v74
	v_fma_f32 v59, -v59, v71, v70
	v_div_fmas_f32 v59, v59, v74, v71
	v_div_fixup_f32 v58, v59, v58, 1.0
	v_mul_f32_e32 v70, 0.5, v58
	v_pk_mul_f32 v[68:69], v[70:71], v[68:69] op_sel_hi:[0,1]
	v_pk_mul_f32 v[58:59], v[70:71], v[64:65] op_sel_hi:[0,1]
	v_pk_fma_f32 v[58:59], v[0:1], v[58:59], v[44:45]
	v_pk_fma_f32 v[44:45], v[2:3], v[68:69], v[46:47]
	v_pk_mul_f32 v[64:65], v[70:71], v[66:67] op_sel_hi:[0,1]
	v_pk_mul_f32 v[46:47], v[70:71], v[62:63] op_sel_hi:[0,1]
	v_pk_fma_f32 v[46:47], v[4:5], v[46:47], v[40:41]
	v_pk_fma_f32 v[40:41], v[6:7], v[64:65], v[42:43]
	v_pk_mul_f32 v[62:63], v[70:71], v[76:77] op_sel_hi:[0,1]
	v_pk_mul_f32 v[42:43], v[70:71], v[60:61] op_sel_hi:[0,1]
	s_waitcnt vmcnt(0)
	v_pk_fma_f32 v[42:43], v[8:9], v[42:43], v[36:37]
	v_pk_fma_f32 v[36:37], v[10:11], v[62:63], v[38:39]
	v_pk_mul_f32 v[50:51], v[70:71], v[50:51] op_sel_hi:[0,1]
	v_pk_mul_f32 v[38:39], v[70:71], v[48:49] op_sel_hi:[0,1]
	v_pk_fma_f32 v[38:39], v[12:13], v[38:39], v[32:33]
	v_pk_fma_f32 v[32:33], v[14:15], v[50:51], v[34:35]
	s_and_b64 vcc, exec, s[0:1]
	s_cbranch_vccnz .LBB0_405
	s_mov_b64 s[6:7], 0

.LBB0_407:
	v_mul_f32_e32 v34, v58, v58
	v_mul_f32_e32 v35, v44, v44
	v_fmac_f32_e32 v34, v59, v59
	v_fmac_f32_e32 v35, v45, v45
	v_add_f32_e32 v34, v35, v34
	v_mul_f32_e32 v35, v46, v46
	v_mul_f32_e32 v48, v40, v40
	v_fmac_f32_e32 v35, v47, v47
	v_fmac_f32_e32 v48, v41, v41
	v_add_f32_e32 v35, v48, v35
	v_add_f32_e32 v34, v35, v34
	v_mul_f32_e32 v35, v42, v42
	v_mul_f32_e32 v48, v36, v36
	v_fmac_f32_e32 v35, v43, v43
	v_fmac_f32_e32 v48, v37, v37
	v_add_f32_e32 v35, v48, v35
	v_add_f32_e32 v34, v35, v34
	v_mul_f32_e32 v35, v38, v38
	v_mul_f32_e32 v48, v32, v32
	v_fmac_f32_e32 v35, v39, v39
	v_fmac_f32_e32 v48, v33, v33
	v_add_f32_e32 v35, v48, v35
	v_add_f32_e32 v34, v35, v34
	s_nop 1
	s_andn2_b64 vcc, exec, s[0:1]
	s_waitcnt lgkmcnt(0)
	v_add_f32_dpp v34, v34, v34 quad_perm:[1,0,3,2] row_mask:0xf bank_mask:0xf
	s_nop 1
	s_waitcnt lgkmcnt(0)
	v_add_f32_dpp v34, v34, v34 quad_perm:[2,3,0,1] row_mask:0xf bank_mask:0xf
	s_nop 1
	s_waitcnt lgkmcnt(0)
	v_add_f32_dpp v34, v34, v34 row_half_mirror row_mask:0xf bank_mask:0xf
	s_nop 1
	s_waitcnt lgkmcnt(0)
	v_add_f32_dpp v34, v34, v34 row_mirror row_mask:0xf bank_mask:0xf
	ds_bpermute_b32 v35, v92, v34
	s_waitcnt lgkmcnt(0)
	v_add_f32_e32 v34, v34, v35
	ds_bpermute_b32 v35, v93, v34
	s_cbranch_vccnz .LBB0_402
	s_waitcnt lgkmcnt(0)
	v_add_f32_e32 v34, v34, v35
	v_fmamk_f32 v34, v34, 0x3a800000, v94
	v_mul_f32_e32 v35, 0x4f800000, v34
	v_cmp_gt_f32_e32 vcc, s10, v34
	s_ashr_i32 s5, s4, 31
	s_nop 0
	v_cndmask_b32_e32 v34, v34, v35, vcc
	v_sqrt_f32_e32 v35, v34
	s_nop 0
	v_add_u32_e32 v48, -1, v35
	v_fma_f32 v50, -v48, v35, v34
	v_add_u32_e32 v49, 1, v35
	v_cmp_ge_f32_e64 s[0:1], 0, v50
	s_nop 1
	v_cndmask_b32_e64 v48, v35, v48, s[0:1]
	v_fma_f32 v35, -v49, v35, v34
	v_cmp_lt_f32_e64 s[0:1], 0, v35
	s_nop 1
	v_cndmask_b32_e64 v35, v48, v49, s[0:1]
	v_mul_f32_e32 v48, 0x37800000, v35
	v_cndmask_b32_e32 v35, v35, v48, vcc
	v_cmp_class_f32_e32 vcc, v34, v95
	s_nop 1
	v_cndmask_b32_e32 v34, v35, v34, vcc
	v_div_scale_f32 v35, s[0:1], v34, v34, 1.0
	v_rcp_f32_e32 v48, v35
	s_lshl_b64 s[0:1], s[4:5], 11
	v_fma_f32 v49, -v35, v48, 1.0
	v_fmac_f32_e32 v48, v49, v48
	v_div_scale_f32 v49, vcc, 1.0, v34, 1.0
	v_mul_f32_e32 v50, v49, v48
	v_fma_f32 v51, -v35, v50, v49
	v_fmac_f32_e32 v50, v51, v48
	v_fma_f32 v35, -v35, v50, v49
	v_div_fmas_f32 v35, v35, v48, v50
	v_div_fixup_f32 v34, v35, v34, 1.0
	v_pk_mul_f32 v[32:33], v[32:33], v[34:35] op_sel_hi:[1,0]
	v_pk_mul_f32 v[38:39], v[38:39], v[34:35] op_sel_hi:[1,0]
	v_pk_mul_f32 v[48:49], v[30:31], v[32:33]
	v_pk_mul_f32 v[32:33], v[42:43], v[34:35] op_sel_hi:[1,0]
	v_pk_mul_f32 v[36:37], v[36:37], v[34:35] op_sel_hi:[1,0]
	v_pk_mul_f32 v[42:43], v[24:25], v[32:33]
	v_pk_mul_f32 v[32:33], v[46:47], v[34:35] op_sel_hi:[1,0]
	v_pk_mul_f32 v[40:41], v[40:41], v[34:35] op_sel_hi:[1,0]
	v_pk_mul_f32 v[46:47], v[20:21], v[32:33]
	v_pk_mul_f32 v[32:33], v[58:59], v[34:35] op_sel_hi:[1,0]
	v_pk_mul_f32 v[34:35], v[44:45], v[34:35] op_sel_hi:[1,0]
	v_pk_mul_f32 v[32:33], v[16:17], v[32:33]
	v_pk_mul_f32 v[34:35], v[18:19], v[34:35]
	v_pk_mul_f32 v[40:41], v[22:23], v[40:41]
	v_lshl_add_u64 v[44:45], v[54:55], 0, s[0:1]
	v_cvt_pk_bf16_f32 v32, v32, v33
	v_cvt_pk_bf16_f32 v33, v34, v35
	v_cvt_pk_bf16_f32 v34, v46, v47
	v_cvt_pk_bf16_f32 v35, v40, v41
	v_pk_mul_f32 v[38:39], v[28:29], v[38:39]
	v_pk_mul_f32 v[36:37], v[26:27], v[36:37]
	global_store_dwordx4 v[44:45], v[32:35], off
	s_nop 1
	v_cvt_pk_bf16_f32 v32, v42, v43
	v_cvt_pk_bf16_f32 v33, v36, v37
	v_cvt_pk_bf16_f32 v34, v38, v39
	v_cvt_pk_bf16_f32 v35, v48, v49
	global_store_dwordx4 v[44:45], v[32:35], off offset:1024
	s_branch .LBB0_402

.LBB0_1202:
	s_ashr_i32 s1, s0, 31
	s_mul_i32 s10, s0, 0x2c00
	s_mul_hi_i32 s11, s0, 0x2c00
	s_add_u32 s10, s4, s10
	s_addc_u32 s11, s5, s11
	v_lshl_add_u64 v[16:17], s[10:11], 0, v[36:37]
	s_lshl_b64 s[16:17], s[0:1], 11
	v_add_co_u32_e32 v20, vcc, 0x2000, v16
	v_lshl_add_u64 v[18:19], v[38:39], 0, s[16:17]
	s_nop 0
	v_addc_co_u32_e32 v21, vcc, 0, v17, vcc
	global_load_dwordx4 v[50:53], v[20:21], off
	global_load_dwordx4 v[24:27], v[18:19], off offset:1024
	v_add_co_u32_e32 v20, vcc, s13, v16
	global_load_dwordx4 v[46:49], v[18:19], off
	s_nop 0
	v_addc_co_u32_e32 v21, vcc, 0, v17, vcc
	global_load_dwordx4 v[42:45], v[20:21], off offset:2048
	v_lshl_add_u64 v[20:21], v[16:17], 0, s[6:7]
	v_lshl_add_u64 v[16:17], v[16:17], 0, s[8:9]
	global_load_dwordx4 v[32:35], v[16:17], off offset:1024
	s_waitcnt lgkmcnt(0)
	global_load_dwordx4 v[28:31], v[20:21], off offset:1024
	s_add_i32 s15, s0, s83
	s_min_i32 s0, s15, 0xffff
	s_ashr_i32 s1, s0, 31
	s_mul_i32 s16, s0, 0x2c00
	s_mul_hi_i32 s17, s0, 0x2c00
	s_add_u32 s16, s4, s16
	s_addc_u32 s17, s5, s17
	v_lshl_add_u64 v[54:55], s[16:17], 0, v[36:37]
	v_add_co_u32_e32 v58, vcc, s12, v54
	s_lshl_b64 s[0:1], s[0:1], 11
	s_nop 0
	v_addc_co_u32_e32 v59, vcc, 0, v55, vcc
	v_add_co_u32_e32 v60, vcc, s13, v54
	s_cmp_gt_i32 s15, 0xffff
	s_nop 0
	v_addc_co_u32_e32 v61, vcc, 0, v55, vcc
	global_load_dwordx4 v[16:19], v[58:59], off
	global_load_dwordx4 v[20:23], v[60:61], off offset:2048
	v_lshl_add_u64 v[96:97], v[38:39], 0, s[0:1]
	global_load_dwordx4 v[80:83], v[96:97], off
	v_lshl_add_u64 v[98:99], v[54:55], 0, s[6:7]
	global_load_dwordx4 v[84:87], v[98:99], off offset:1024
	v_lshl_add_u64 v[98:99], v[54:55], 0, s[8:9]
	global_load_dwordx4 v[88:91], v[98:99], off offset:1024
	global_load_dwordx4 v[92:95], v[96:97], off offset:1024
	s_waitcnt vmcnt(4)
	v_lshlrev_b32_e32 v70, 16, v50
	v_and_b32_e32 v71, 0xffff0000, v50
	v_lshlrev_b32_e32 v50, 16, v51
	v_and_b32_e32 v51, 0xffff0000, v51
	v_lshlrev_b32_e32 v58, 16, v46
	v_and_b32_e32 v59, 0xffff0000, v46
	v_lshlrev_b32_e32 v46, 16, v47
	v_and_b32_e32 v47, 0xffff0000, v47
	v_lshlrev_b32_e32 v60, 16, v48
	v_and_b32_e32 v61, 0xffff0000, v48
	v_lshlrev_b32_e32 v72, 16, v52
	v_and_b32_e32 v73, 0xffff0000, v52
	v_lshlrev_b32_e32 v74, 16, v42
	v_and_b32_e32 v75, 0xffff0000, v42
	v_lshlrev_b32_e32 v42, 16, v43
	v_and_b32_e32 v43, 0xffff0000, v43
	v_pk_add_f32 v[46:47], v[50:51], v[46:47]
	v_lshlrev_b32_e32 v50, 16, v44
	v_and_b32_e32 v51, 0xffff0000, v44
	v_pk_add_f32 v[58:59], v[70:71], v[58:59]
	v_pk_add_f32 v[60:61], v[72:73], v[60:61]
	v_lshlrev_b32_e32 v70, 16, v45
	v_and_b32_e32 v71, 0xffff0000, v45
	v_mul_f32_e32 v44, 0xbfb8aa3b, v74
	v_mul_f32_e32 v45, 0xbfb8aa3b, v75
	v_mul_f32_e32 v48, 0xbfb8aa3b, v42
	v_mul_f32_e32 v56, 0xbfb8aa3b, v43
	v_mul_f32_e32 v72, 0xbfb8aa3b, v50
	v_mul_f32_e32 v73, 0xbfb8aa3b, v51
	v_exp_f32_e32 v44, v44
	v_exp_f32_e32 v45, v45
	v_exp_f32_e32 v48, v48
	v_exp_f32_e32 v56, v56
	v_exp_f32_e32 v72, v72
	v_exp_f32_e32 v73, v73
	v_add_f32_e32 v44, 1.0, v44
	v_add_f32_e32 v45, 1.0, v45
	v_add_f32_e32 v48, 1.0, v48
	v_add_f32_e32 v56, 1.0, v56
	v_add_f32_e32 v76, 1.0, v72
	v_add_f32_e32 v77, 1.0, v73
	v_rcp_f32_e32 v44, v44
	v_rcp_f32_e32 v45, v45
	v_rcp_f32_e32 v72, v48
	v_rcp_f32_e32 v73, v56
	v_rcp_f32_e32 v76, v76
	v_rcp_f32_e32 v77, v77
	v_mul_f32_e32 v78, 0xbfb8aa3b, v70
	v_pk_mul_f32 v[44:45], v[44:45], v[74:75]
	v_pk_mul_f32 v[72:73], v[72:73], v[42:43]
	v_pk_mul_f32 v[50:51], v[76:77], v[50:51]
	v_exp_f32_e32 v48, v78
	v_pk_mul_f32 v[42:43], v[58:59], v[44:45]
	v_pk_mul_f32 v[44:45], v[46:47], v[72:73]
	v_pk_mul_f32 v[46:47], v[60:61], v[50:51]
	v_mul_f32_e32 v50, 0xbfb8aa3b, v71
	v_exp_f32_e32 v51, v50
	v_add_f32_e32 v48, 1.0, v48
	v_rcp_f32_e32 v50, v48
	v_lshlrev_b32_e32 v52, 16, v53
	v_add_f32_e32 v48, 1.0, v51
	v_rcp_f32_e32 v51, v48
	v_and_b32_e32 v53, 0xffff0000, v53
	v_lshlrev_b32_e32 v48, 16, v49
	v_and_b32_e32 v49, 0xffff0000, v49
	v_pk_add_f32 v[48:49], v[52:53], v[48:49]
	v_lshlrev_b32_e32 v52, 16, v32
	v_pk_mul_f32 v[50:51], v[50:51], v[70:71]
	v_and_b32_e32 v53, 0xffff0000, v32
	v_mul_f32_e32 v32, 0xbfb8aa3b, v52
	v_pk_mul_f32 v[48:49], v[48:49], v[50:51]
	v_exp_f32_e32 v32, v32
	v_mul_f32_e32 v51, 0xbfb8aa3b, v53
	v_exp_f32_e32 v56, v51
	v_lshlrev_b32_e32 v50, 16, v28
	v_and_b32_e32 v51, 0xffff0000, v28
	v_add_f32_e32 v28, 1.0, v32
	v_rcp_f32_e32 v58, v28
	v_add_f32_e32 v28, 1.0, v56
	v_rcp_f32_e32 v59, v28
	v_lshlrev_b32_e32 v60, 16, v24
	v_and_b32_e32 v61, 0xffff0000, v24
	v_lshlrev_b32_e32 v32, 16, v33
	v_pk_add_f32 v[50:51], v[50:51], v[60:61]
	v_pk_mul_f32 v[52:53], v[58:59], v[52:53]
	v_and_b32_e32 v33, 0xffff0000, v33
	v_mul_f32_e32 v24, 0xbfb8aa3b, v32
	v_pk_mul_f32 v[50:51], v[50:51], v[52:53]
	v_exp_f32_e32 v24, v24
	v_mul_f32_e32 v52, 0xbfb8aa3b, v33
	v_exp_f32_e32 v53, v52
	v_lshlrev_b32_e32 v28, 16, v29
	v_add_f32_e32 v24, 1.0, v24
	v_rcp_f32_e32 v52, v24
	v_add_f32_e32 v24, 1.0, v53
	v_rcp_f32_e32 v53, v24
	v_and_b32_e32 v29, 0xffff0000, v29
	v_lshlrev_b32_e32 v24, 16, v25
	v_and_b32_e32 v25, 0xffff0000, v25
	v_pk_add_f32 v[24:25], v[28:29], v[24:25]
	v_pk_mul_f32 v[28:29], v[52:53], v[32:33]
	v_lshlrev_b32_e32 v58, 16, v26
	v_pk_mul_f32 v[52:53], v[24:25], v[28:29]
	v_lshlrev_b32_e32 v28, 16, v34
	v_and_b32_e32 v29, 0xffff0000, v34
	v_mul_f32_e32 v25, 0xbfb8aa3b, v28
	v_exp_f32_e32 v32, v25
	v_mul_f32_e32 v25, 0xbfb8aa3b, v29
	v_exp_f32_e32 v33, v25
	v_lshlrev_b32_e32 v24, 16, v30
	v_and_b32_e32 v25, 0xffff0000, v30
	v_add_f32_e32 v30, 1.0, v32
	v_rcp_f32_e32 v32, v30
	v_add_f32_e32 v30, 1.0, v33
	v_rcp_f32_e32 v33, v30
	v_and_b32_e32 v59, 0xffff0000, v26
	v_pk_add_f32 v[24:25], v[24:25], v[58:59]
	v_pk_mul_f32 v[28:29], v[32:33], v[28:29]
	s_nop 0
	v_pk_mul_f32 v[58:59], v[24:25], v[28:29]
	v_lshlrev_b32_e32 v28, 16, v35
	v_and_b32_e32 v29, 0xffff0000, v35
	v_mul_f32_e32 v25, 0xbfb8aa3b, v28
	v_exp_f32_e32 v26, v25
	v_mul_f32_e32 v25, 0xbfb8aa3b, v29
	v_exp_f32_e32 v32, v25
	v_lshlrev_b32_e32 v24, 16, v31
	v_add_f32_e32 v26, 1.0, v26
	v_rcp_f32_e32 v30, v26
	v_add_f32_e32 v26, 1.0, v32
	v_and_b32_e32 v25, 0xffff0000, v31
	v_rcp_f32_e32 v31, v26
	v_lshlrev_b32_e32 v26, 16, v27
	v_and_b32_e32 v27, 0xffff0000, v27
	v_pk_add_f32 v[24:25], v[24:25], v[26:27]
	v_pk_mul_f32 v[26:27], v[30:31], v[28:29]
	v_mov_b32_e32 v28, v47
	v_pk_mul_f32 v[74:75], v[24:25], v[26:27]
	v_mov_b32_e32 v26, v43
	v_mov_b32_e32 v27, v45
	v_mov_b32_e32 v24, v42
	v_mov_b32_e32 v25, v44
	v_pk_mul_f32 v[26:27], v[26:27], v[26:27]
	v_mov_b32_e32 v29, v49
	v_pk_fma_f32 v[24:25], v[24:25], v[24:25], v[26:27]
	v_mov_b32_e32 v26, v46
	v_pk_add_f32 v[24:25], v[24:25], v[24:25] op_sel_hi:[0,1]
	v_mov_b32_e32 v27, v48
	v_pk_mul_f32 v[28:29], v[28:29], v[28:29]
	v_mul_f32_e32 v24, v50, v50
	v_pk_fma_f32 v[26:27], v[26:27], v[26:27], v[28:29]
	v_pk_fma_f32 v[28:29], v[50:51], v[50:51], v[24:25] op_sel_hi:[1,1,0]
	v_mul_f32_e32 v24, v52, v52
	v_pk_add_f32 v[26:27], v[26:27], v[26:27] op_sel_hi:[0,1]
	v_pk_fma_f32 v[30:31], v[52:53], v[52:53], v[24:25] op_sel_hi:[1,1,0]
	v_pk_mul_f32 v[32:33], v[58:59], v[58:59]
	v_pk_mul_f32 v[34:35], v[74:75], v[74:75]
	v_mov_b32_e32 v24, v32
	v_mov_b32_e32 v26, v33
	v_mov_b32_e32 v28, v34
	v_mov_b32_e32 v30, v35
	v_pk_add_f32 v[24:25], v[24:25], v[26:27]
	v_pk_add_f32 v[26:27], v[28:29], v[30:31]
	s_nop 0
	v_pk_add_f32 v[24:25], v[24:25], v[26:27]
	s_nop 0
	v_add_f32_e32 v24, v24, v25
	s_nop 1
	s_waitcnt lgkmcnt(0)
	v_add_f32_dpp v24, v24, v24 quad_perm:[1,0,3,2] row_mask:0xf bank_mask:0xf
	s_nop 1
	s_waitcnt lgkmcnt(0)
	v_add_f32_dpp v24, v24, v24 quad_perm:[2,3,0,1] row_mask:0xf bank_mask:0xf
	s_nop 1
	s_waitcnt lgkmcnt(0)
	v_add_f32_dpp v24, v24, v24 row_half_mirror row_mask:0xf bank_mask:0xf
	s_nop 1
	s_waitcnt lgkmcnt(0)
	v_add_f32_dpp v24, v24, v24 row_mirror row_mask:0xf bank_mask:0xf
	ds_bpermute_b32 v25, v65, v24
	s_waitcnt lgkmcnt(0)
	v_add_f32_e32 v24, v24, v25
	ds_bpermute_b32 v25, v66, v24
	s_waitcnt lgkmcnt(0)
	v_add_f32_e32 v24, v24, v25
	v_fmamk_f32 v24, v24, 0x3a800000, v67
	v_mul_f32_e32 v25, 0x4f800000, v24
	v_cmp_gt_f32_e32 vcc, s14, v24
	s_nop 1
	v_cndmask_b32_e32 v30, v24, v25, vcc
	v_sqrt_f32_e32 v31, v30
	s_nop 0
	s_nop 0
	v_add_u32_e32 v32, -1, v31
	v_fma_f32 v33, -v32, v31, v30
	v_cmp_ge_f32_e64 s[0:1], 0, v33
	v_add_u32_e32 v33, 1, v31
	s_waitcnt vmcnt(3)
	v_mov_b32_e32 v70, v80
	v_mov_b32_e32 v71, v81
	v_mov_b32_e32 v72, v82
	v_mov_b32_e32 v73, v83
	v_lshlrev_b32_e32 v78, 16, v70
	v_cndmask_b32_e64 v32, v31, v32, s[0:1]
	v_fma_f32 v31, -v33, v31, v30
	v_cmp_lt_f32_e64 s[0:1], 0, v31
	v_and_b32_e32 v79, 0xffff0000, v70
	s_nop 0
	v_cndmask_b32_e64 v31, v32, v33, s[0:1]
	v_mul_f32_e32 v32, 0x37800000, v31
	v_cndmask_b32_e32 v31, v31, v32, vcc
	v_cmp_class_f32_e32 vcc, v30, v68
	s_nop 0
	s_nop 0
	v_cndmask_b32_e32 v56, v31, v30, vcc
	s_nop 0
	v_div_scale_f32 v60, s[0:1], v56, v56, 1.0
	v_rcp_f32_e32 v61, v60
	s_nop 0
	v_fma_f32 v54, -v60, v61, 1.0
	v_fmac_f32_e32 v61, v54, v61
	v_div_scale_f32 v54, vcc, 1.0, v56, 1.0
	v_mul_f32_e32 v55, v54, v61
	v_fma_f32 v76, -v60, v55, v54
	v_fmac_f32_e32 v55, v76, v61
	v_fma_f32 v54, -v60, v55, v54
	v_div_fmas_f32 v54, v54, v61, v55
	v_div_fixup_f32 v56, v54, v56, 1.0
	v_pk_mul_f32 v[54:55], v[74:75], v[56:57] op_sel_hi:[1,0]
	v_lshlrev_b32_e32 v74, 16, v20
	v_and_b32_e32 v75, 0xffff0000, v20
	v_mul_f32_e32 v20, 0xbfb8aa3b, v74
	v_pk_mul_f32 v[60:61], v[58:59], v[56:57] op_sel_hi:[1,0]
	v_exp_f32_e32 v20, v20
	v_mul_f32_e32 v59, 0xbfb8aa3b, v75
	v_exp_f32_e32 v77, v59
	v_lshlrev_b32_e32 v58, 16, v16
	v_and_b32_e32 v59, 0xffff0000, v16
	v_add_f32_e32 v16, 1.0, v20
	v_rcp_f32_e32 v76, v16
	v_add_f32_e32 v16, 1.0, v77
	v_rcp_f32_e32 v77, v16
	v_lshlrev_b32_e32 v20, 16, v21
	v_pk_add_f32 v[58:59], v[58:59], v[78:79]
	v_and_b32_e32 v21, 0xffff0000, v21
	v_pk_mul_f32 v[74:75], v[76:77], v[74:75]
	v_mul_f32_e32 v70, 0xbfb8aa3b, v20
	v_pk_mul_f32 v[58:59], v[58:59], v[74:75]
	v_exp_f32_e32 v70, v70
	v_mul_f32_e32 v74, 0xbfb8aa3b, v21
	v_exp_f32_e32 v75, v74
	v_lshlrev_b32_e32 v16, 16, v17
	v_add_f32_e32 v70, 1.0, v70
	v_rcp_f32_e32 v74, v70
	v_add_f32_e32 v70, 1.0, v75
	v_rcp_f32_e32 v75, v70
	v_and_b32_e32 v17, 0xffff0000, v17
	v_lshlrev_b32_e32 v70, 16, v71
	v_and_b32_e32 v71, 0xffff0000, v71
	v_pk_add_f32 v[16:17], v[16:17], v[70:71]
	v_pk_mul_f32 v[20:21], v[74:75], v[20:21]
	v_lshlrev_b32_e32 v70, 16, v22
	v_pk_mul_f32 v[16:17], v[16:17], v[20:21]
	v_and_b32_e32 v71, 0xffff0000, v22
	v_mul_f32_e32 v21, 0xbfb8aa3b, v70
	v_exp_f32_e32 v22, v21
	v_mul_f32_e32 v21, 0xbfb8aa3b, v71
	v_exp_f32_e32 v75, v21
	v_lshlrev_b32_e32 v20, 16, v18
	v_and_b32_e32 v21, 0xffff0000, v18
	v_add_f32_e32 v18, 1.0, v22
	v_rcp_f32_e32 v74, v18
	v_add_f32_e32 v18, 1.0, v75
	v_rcp_f32_e32 v75, v18
	v_lshlrev_b32_e32 v76, 16, v72
	v_and_b32_e32 v77, 0xffff0000, v72
	v_pk_add_f32 v[20:21], v[20:21], v[76:77]
	v_pk_mul_f32 v[70:71], v[74:75], v[70:71]
	v_lshlrev_b32_e32 v22, 16, v23
	v_and_b32_e32 v23, 0xffff0000, v23
	v_pk_mul_f32 v[20:21], v[20:21], v[70:71]
	v_mul_f32_e32 v70, 0xbfb8aa3b, v22
	v_mul_f32_e32 v71, 0xbfb8aa3b, v23
	v_exp_f32_e32 v70, v70
	v_exp_f32_e32 v71, v71
	v_lshlrev_b32_e32 v18, 16, v19
	v_and_b32_e32 v19, 0xffff0000, v19
	v_add_f32_e32 v70, 1.0, v70
	v_add_f32_e32 v71, 1.0, v71
	v_rcp_f32_e32 v70, v70
	v_rcp_f32_e32 v71, v71
	v_lshlrev_b32_e32 v72, 16, v73
	v_and_b32_e32 v73, 0xffff0000, v73
	v_pk_add_f32 v[18:19], v[18:19], v[72:73]
	v_pk_mul_f32 v[22:23], v[70:71], v[22:23]
	s_waitcnt vmcnt(1)
	v_mov_b32_e32 v24, v84
	v_mov_b32_e32 v25, v85
	v_mov_b32_e32 v26, v86
	v_mov_b32_e32 v27, v87
	v_mov_b32_e32 v32, v88
	v_mov_b32_e32 v33, v89
	v_mov_b32_e32 v34, v90
	v_mov_b32_e32 v35, v91
	v_lshlrev_b32_e32 v70, 16, v32
	v_pk_mul_f32 v[18:19], v[18:19], v[22:23]
	v_and_b32_e32 v71, 0xffff0000, v32
	v_mul_f32_e32 v23, 0xbfb8aa3b, v70
	v_exp_f32_e32 v32, v23
	v_mul_f32_e32 v23, 0xbfb8aa3b, v71
	v_exp_f32_e32 v73, v23
	v_lshlrev_b32_e32 v22, 16, v24
	v_and_b32_e32 v23, 0xffff0000, v24
	v_add_f32_e32 v24, 1.0, v32
	v_rcp_f32_e32 v72, v24
	v_add_f32_e32 v24, 1.0, v73
	v_rcp_f32_e32 v73, v24
	s_waitcnt vmcnt(0)
	v_mov_b32_e32 v28, v92
	v_mov_b32_e32 v29, v93
	v_mov_b32_e32 v30, v94
	v_mov_b32_e32 v31, v95
	v_lshlrev_b32_e32 v74, 16, v28
	v_and_b32_e32 v75, 0xffff0000, v28
	v_lshlrev_b32_e32 v32, 16, v33
	v_pk_add_f32 v[22:23], v[22:23], v[74:75]
	v_pk_mul_f32 v[70:71], v[72:73], v[70:71]
	v_and_b32_e32 v33, 0xffff0000, v33
	v_mul_f32_e32 v28, 0xbfb8aa3b, v32
	v_pk_mul_f32 v[22:23], v[22:23], v[70:71]
	v_exp_f32_e32 v28, v28
	v_mul_f32_e32 v70, 0xbfb8aa3b, v33
	v_exp_f32_e32 v71, v70
	v_lshlrev_b32_e32 v24, 16, v25
	v_add_f32_e32 v28, 1.0, v28
	v_rcp_f32_e32 v70, v28
	v_add_f32_e32 v28, 1.0, v71
	v_rcp_f32_e32 v71, v28
	v_and_b32_e32 v25, 0xffff0000, v25
	v_lshlrev_b32_e32 v28, 16, v29
	v_and_b32_e32 v29, 0xffff0000, v29
	v_pk_add_f32 v[24:25], v[24:25], v[28:29]
	v_pk_mul_f32 v[28:29], v[70:71], v[32:33]
	v_lshlrev_b32_e32 v32, 16, v34
	v_pk_mul_f32 v[24:25], v[24:25], v[28:29]
	v_and_b32_e32 v33, 0xffff0000, v34
	v_mul_f32_e32 v29, 0xbfb8aa3b, v32
	v_exp_f32_e32 v34, v29
	v_mul_f32_e32 v29, 0xbfb8aa3b, v33
	v_exp_f32_e32 v71, v29
	v_lshlrev_b32_e32 v28, 16, v26
	v_and_b32_e32 v29, 0xffff0000, v26
	v_add_f32_e32 v26, 1.0, v34
	v_rcp_f32_e32 v70, v26
	v_add_f32_e32 v26, 1.0, v71
	v_rcp_f32_e32 v71, v26
	v_lshlrev_b32_e32 v72, 16, v30
	v_and_b32_e32 v73, 0xffff0000, v30
	v_pk_add_f32 v[28:29], v[28:29], v[72:73]
	v_pk_mul_f32 v[32:33], v[70:71], v[32:33]
	v_lshlrev_b32_e32 v26, 16, v27
	v_pk_mul_f32 v[28:29], v[28:29], v[32:33]
	v_lshlrev_b32_e32 v32, 16, v35
	v_and_b32_e32 v33, 0xffff0000, v35
	v_mul_f32_e32 v30, 0xbfb8aa3b, v32
	v_exp_f32_e32 v30, v30
	v_mul_f32_e32 v34, 0xbfb8aa3b, v33
	v_exp_f32_e32 v35, v34
	v_and_b32_e32 v27, 0xffff0000, v27
	v_add_f32_e32 v30, 1.0, v30
	v_rcp_f32_e32 v34, v30
	v_add_f32_e32 v30, 1.0, v35
	v_rcp_f32_e32 v35, v30
	v_lshlrev_b32_e32 v30, 16, v31
	v_and_b32_e32 v31, 0xffff0000, v31
	v_pk_add_f32 v[26:27], v[26:27], v[30:31]
	v_pk_mul_f32 v[30:31], v[34:35], v[32:33]
	v_pk_mul_f32 v[32:33], v[16:17], v[16:17]
	v_pk_mul_f32 v[26:27], v[26:27], v[30:31]
	v_pk_mul_f32 v[30:31], v[58:59], v[58:59]
	v_pk_mul_f32 v[34:35], v[20:21], v[20:21]
	v_pk_mul_f32 v[70:71], v[18:19], v[18:19]
	v_pk_mul_f32 v[72:73], v[22:23], v[22:23]
	v_pk_mul_f32 v[74:75], v[24:25], v[24:25]
	v_add_f32_e32 v70, v70, v71
	v_add_f32_e32 v34, v34, v35
	v_add_f32_e32 v32, v32, v33
	v_add_f32_e32 v30, v30, v31
	v_add_f32_e32 v34, v34, v70
	v_add_f32_e32 v30, v30, v32
	v_add_f32_e32 v31, v74, v75
	v_add_f32_e32 v32, v72, v73
	v_pk_mul_f32 v[76:77], v[28:29], v[28:29]
	v_pk_mul_f32 v[78:79], v[26:27], v[26:27]
	v_add_f32_e32 v30, v30, v34
	v_add_f32_e32 v31, v32, v31
	v_add_f32_e32 v30, v30, v31
	v_add_f32_e32 v31, v78, v79
	v_add_f32_e32 v32, v76, v77
	v_add_f32_e32 v31, v32, v31
	v_add_f32_e32 v70, v31, v30
	s_nop 1
	v_pk_mul_f32 v[34:35], v[12:13], v[60:61]
	v_pk_mul_f32 v[32:33], v[52:53], v[56:57] op_sel_hi:[1,0]
	v_pk_mul_f32 v[30:31], v[50:51], v[56:57] op_sel_hi:[1,0]
	v_pk_mul_f32 v[50:51], v[10:11], v[32:33]
	s_waitcnt lgkmcnt(0)
	v_add_f32_dpp v60, v70, v70 quad_perm:[1,0,3,2] row_mask:0xf bank_mask:0xf
	s_nop 1
	v_pk_mul_f32 v[32:33], v[48:49], v[56:57] op_sel_hi:[1,0]
	v_pk_mul_f32 v[52:53], v[8:9], v[30:31]
	v_pk_mul_f32 v[30:31], v[46:47], v[56:57] op_sel_hi:[1,0]
	v_pk_mul_f32 v[46:47], v[6:7], v[32:33]
	s_waitcnt lgkmcnt(0)
	v_add_f32_dpp v48, v60, v60 quad_perm:[2,3,0,1] row_mask:0xf bank_mask:0xf
	s_nop 1
	v_pk_mul_f32 v[32:33], v[4:5], v[30:31]
	v_pk_mul_f32 v[30:31], v[42:43], v[56:57] op_sel_hi:[1,0]
	v_pk_mul_f32 v[42:43], v[44:45], v[56:57] op_sel_hi:[1,0]
	v_pk_mul_f32 v[30:31], v[0:1], v[30:31]
	s_waitcnt lgkmcnt(0)
	v_add_f32_dpp v44, v48, v48 row_half_mirror row_mask:0xf bank_mask:0xf
	s_nop 1
	v_pk_mul_f32 v[42:43], v[2:3], v[42:43]
	v_cvt_pk_bf16_f32 v30, v30, v31
	v_pk_mul_f32 v[54:55], v[14:15], v[54:55]
	v_cvt_pk_bf16_f32 v31, v42, v43
	s_waitcnt lgkmcnt(0)
	v_add_f32_dpp v42, v44, v44 row_mirror row_mask:0xf bank_mask:0xf
	ds_bpermute_b32 v43, v65, v42
	v_cvt_pk_bf16_f32 v32, v32, v33
	v_cvt_pk_bf16_f32 v33, v46, v47
	global_store_dwordx4 v36, v[30:33], s[10:11] offset:2048
	s_waitcnt lgkmcnt(0)
	s_nop 0
	v_add_f32_e32 v30, v42, v43
	ds_bpermute_b32 v31, v66, v30
	v_cvt_pk_bf16_f32 v32, v52, v53
	v_cvt_pk_bf16_f32 v33, v50, v51
	v_cvt_pk_bf16_f32 v34, v34, v35
	v_cvt_pk_bf16_f32 v35, v54, v55
	global_store_dwordx4 v36, v[32:35], s[10:11] offset:3072
	s_cbranch_scc1 .LBB0_1201
	s_waitcnt lgkmcnt(0)
	v_add_f32_e32 v30, v30, v31
	v_fmamk_f32 v30, v30, 0x3a800000, v67
	v_mul_f32_e32 v31, 0x4f800000, v30
	v_cmp_gt_f32_e32 vcc, s14, v30
	s_nop 1
	v_cndmask_b32_e32 v30, v30, v31, vcc
	v_sqrt_f32_e32 v31, v30
	s_nop 0
	v_add_u32_e32 v32, -1, v31
	v_fma_f32 v34, -v32, v31, v30
	v_add_u32_e32 v33, 1, v31
	v_cmp_ge_f32_e64 s[0:1], 0, v34
	s_nop 1
	v_cndmask_b32_e64 v32, v31, v32, s[0:1]
	v_fma_f32 v31, -v33, v31, v30
	v_cmp_lt_f32_e64 s[0:1], 0, v31
	s_nop 1
	v_cndmask_b32_e64 v31, v32, v33, s[0:1]
	v_mul_f32_e32 v32, 0x37800000, v31
	v_cndmask_b32_e32 v31, v31, v32, vcc
	v_cmp_class_f32_e32 vcc, v30, v68
	s_nop 1
	v_cndmask_b32_e32 v30, v31, v30, vcc
	v_div_scale_f32 v31, s[0:1], v30, v30, 1.0
	v_rcp_f32_e32 v32, v31
	s_nop 0
	v_fma_f32 v33, -v31, v32, 1.0
	v_fmac_f32_e32 v32, v33, v32
	v_div_scale_f32 v33, vcc, 1.0, v30, 1.0
	v_mul_f32_e32 v34, v33, v32
	v_fma_f32 v35, -v31, v34, v33
	v_fmac_f32_e32 v34, v35, v32
	v_fma_f32 v31, -v31, v34, v33
	v_div_fmas_f32 v31, v31, v32, v34
	v_div_fixup_f32 v30, v31, v30, 1.0
	v_pk_mul_f32 v[20:21], v[20:21], v[30:31] op_sel_hi:[1,0]
	v_pk_mul_f32 v[18:19], v[18:19], v[30:31] op_sel_hi:[1,0]
	v_pk_mul_f32 v[16:17], v[16:17], v[30:31] op_sel_hi:[1,0]
	v_pk_mul_f32 v[32:33], v[6:7], v[18:19]
	v_pk_mul_f32 v[18:19], v[4:5], v[20:21]
	v_pk_mul_f32 v[20:21], v[58:59], v[30:31] op_sel_hi:[1,0]
	v_pk_mul_f32 v[28:29], v[28:29], v[30:31] op_sel_hi:[1,0]
	v_pk_mul_f32 v[26:27], v[26:27], v[30:31] op_sel_hi:[1,0]
	v_pk_mul_f32 v[22:23], v[22:23], v[30:31] op_sel_hi:[1,0]
	v_pk_mul_f32 v[24:25], v[24:25], v[30:31] op_sel_hi:[1,0]
	v_pk_mul_f32 v[30:31], v[2:3], v[16:17]
	v_pk_mul_f32 v[16:17], v[0:1], v[20:21]
	v_mad_i64_i32 v[20:21], s[0:1], s15, v69, v[40:41]
	v_cvt_pk_bf16_f32 v16, v16, v17
	v_cvt_pk_bf16_f32 v17, v30, v31
	v_cvt_pk_bf16_f32 v18, v18, v19
	v_cvt_pk_bf16_f32 v19, v32, v33
	v_pk_mul_f32 v[26:27], v[14:15], v[26:27]
	v_pk_mul_f32 v[28:29], v[12:13], v[28:29]
	v_pk_mul_f32 v[24:25], v[10:11], v[24:25]
	v_pk_mul_f32 v[22:23], v[8:9], v[22:23]
	global_store_dwordx4 v[20:21], v[16:19], off offset:2048
	s_nop 1
	v_cvt_pk_bf16_f32 v16, v22, v23
	v_cvt_pk_bf16_f32 v17, v24, v25
	v_cvt_pk_bf16_f32 v18, v28, v29
	v_cvt_pk_bf16_f32 v19, v26, v27
	global_store_dwordx4 v[20:21], v[16:19], off offset:3072
	s_branch .LBB0_1201

.LBB0_1339:
	s_ashr_i32 s1, s0, 31
	s_lshl_b64 s[6:7], s[0:1], 11
	v_lshl_add_u64 v[48:49], v[42:43], 0, s[6:7]
	global_load_dwordx4 v[32:35], v[48:49], off offset:1024
	global_load_dwordx4 v[36:39], v[48:49], off
	v_lshl_add_u64 v[48:49], v[40:41], 0, s[6:7]
	global_load_dwordx4 v[52:55], v[48:49], off
	s_waitcnt lgkmcnt(0)
	global_load_dwordx4 v[56:59], v[48:49], off offset:1024
	s_add_i32 s4, s0, s83
	s_min_i32 s0, s4, 0xffff
	s_ashr_i32 s1, s0, 31
	s_lshl_b64 s[0:1], s[0:1], 11
	v_lshl_add_u64 v[76:77], v[42:43], 0, s[0:1]
	v_lshl_add_u64 v[96:97], v[46:47], 0, s[6:7]
	s_cmp_lt_i32 s4, 0x10000
	s_waitcnt vmcnt(0)
	v_lshlrev_b32_e32 v48, 16, v34
	v_lshlrev_b32_e32 v64, 16, v36
	v_lshlrev_b32_e32 v66, 16, v37
	v_and_b32_e32 v71, 0xffff0000, v39
	v_and_b32_e32 v70, 0xffff0000, v38
	v_and_b32_e32 v49, 0xffff0000, v34
	v_and_b32_e32 v65, 0xffff0000, v36
	v_and_b32_e32 v67, 0xffff0000, v37
	v_lshlrev_b32_e32 v69, 16, v39
	v_lshlrev_b32_e32 v68, 16, v38
	v_lshlrev_b32_e32 v72, 16, v32
	v_and_b32_e32 v73, 0xffff0000, v32
	v_lshlrev_b32_e32 v74, 16, v33
	v_mul_f32_e32 v32, v64, v64
	v_mul_f32_e32 v34, v66, v66
	v_pk_mul_f32 v[36:37], v[70:71], v[70:71]
	v_lshlrev_b32_e32 v50, 16, v35
	v_and_b32_e32 v51, 0xffff0000, v35
	v_and_b32_e32 v75, 0xffff0000, v33
	v_mul_f32_e32 v38, v72, v72
	v_mul_f32_e32 v60, v74, v74
	v_pk_fma_f32 v[32:33], v[64:65], v[64:65], v[32:33] op_sel_hi:[1,1,0]
	v_pk_fma_f32 v[34:35], v[66:67], v[66:67], v[34:35] op_sel_hi:[1,1,0]
	v_pk_fma_f32 v[36:37], v[68:69], v[68:69], v[36:37]
	v_pk_fma_f32 v[38:39], v[72:73], v[72:73], v[38:39] op_sel_hi:[1,1,0]
	v_pk_fma_f32 v[60:61], v[74:75], v[74:75], v[60:61] op_sel_hi:[1,1,0]
	v_pk_add_f32 v[36:37], v[36:37], v[36:37] op_sel_hi:[0,1]
	v_pk_add_f32 v[32:33], v[32:33], v[34:35]
	v_mul_f32_e32 v62, v48, v48
	v_mul_f32_e32 v38, v50, v50
	v_mul_f32_e32 v60, v51, v51
	v_mul_f32_e32 v36, v49, v49
	v_mov_b32_e32 v63, v33
	v_pk_add_f32 v[32:33], v[38:39], v[60:61]
	v_pk_add_f32 v[34:35], v[62:63], v[36:37]
	v_lshlrev_b32_e32 v82, 16, v57
	v_pk_add_f32 v[32:33], v[34:35], v[32:33]
	v_and_b32_e32 v99, 0xffff0000, v58
	v_add_f32_e32 v32, v32, v33
	s_nop 1
	v_lshlrev_b32_e32 v100, 16, v59
	s_waitcnt lgkmcnt(0)
	v_add_f32_dpp v34, v32, v32 quad_perm:[1,0,3,2] row_mask:0xf bank_mask:0xf
	s_nop 1
	v_lshl_add_u64 v[32:33], v[40:41], 0, s[0:1]
	global_load_dwordx4 v[60:63], v[32:33], off
	global_load_dwordx4 v[92:95], v[32:33], off offset:1024
	s_waitcnt lgkmcnt(0)
	v_add_f32_dpp v78, v34, v34 quad_perm:[2,3,0,1] row_mask:0xf bank_mask:0xf
	s_nop 1
	global_load_dwordx4 v[36:39], v[76:77], off
	global_load_dwordx4 v[32:35], v[76:77], off offset:1024
	v_lshlrev_b32_e32 v76, 16, v52
	v_and_b32_e32 v77, 0xffff0000, v52
	v_lshlrev_b32_e32 v52, 16, v53
	s_waitcnt lgkmcnt(0)
	v_add_f32_dpp v80, v78, v78 row_half_mirror row_mask:0xf bank_mask:0xf
	s_nop 1
	v_and_b32_e32 v53, 0xffff0000, v53
	v_lshlrev_b32_e32 v78, 16, v54
	v_and_b32_e32 v79, 0xffff0000, v54
	v_lshlrev_b32_e32 v54, 16, v55
	s_waitcnt lgkmcnt(0)
	v_add_f32_dpp v83, v80, v80 row_mirror row_mask:0xf bank_mask:0xf
	ds_bpermute_b32 v98, v88, v83
	v_lshlrev_b32_e32 v80, 16, v56
	v_and_b32_e32 v81, 0xffff0000, v56
	v_and_b32_e32 v55, 0xffff0000, v55
	s_waitcnt lgkmcnt(0)
	v_add_f32_e32 v56, v83, v98
	ds_bpermute_b32 v101, v89, v56
	v_and_b32_e32 v83, 0xffff0000, v57
	v_lshlrev_b32_e32 v98, 16, v58
	s_waitcnt lgkmcnt(0)
	v_add_f32_e32 v56, v56, v101
	v_fmamk_f32 v56, v56, 0x3a800000, v90
	v_mul_f32_e32 v57, 0x4f800000, v56
	v_cmp_gt_f32_e32 vcc, s8, v56
	v_and_b32_e32 v101, 0xffff0000, v59
	s_waitcnt vmcnt(0)
	v_lshlrev_b32_e32 v104, 16, v33
	v_cndmask_b32_e32 v58, v56, v57, vcc
	v_sqrt_f32_e32 v102, v58
	v_mov_b32_e32 v56, v68
	v_mov_b32_e32 v57, v70
	v_and_b32_e32 v105, 0xffff0000, v33
	v_add_u32_e32 v59, -1, v102
	v_add_u32_e32 v68, 1, v102
	v_fma_f32 v70, -v59, v102, v58
	v_fma_f32 v103, -v68, v102, v58
	v_cmp_ge_f32_e64 s[0:1], 0, v70
	v_mov_b32_e32 v70, v69
	s_nop 0
	v_cndmask_b32_e64 v59, v102, v59, s[0:1]
	v_cmp_lt_f32_e64 s[0:1], 0, v103
	s_nop 1
	v_cndmask_b32_e64 v59, v59, v68, s[0:1]
	v_mul_f32_e32 v68, 0x37800000, v59
	v_cndmask_b32_e32 v59, v59, v68, vcc
	v_cmp_class_f32_e32 vcc, v58, v91
	s_nop 1
	v_cndmask_b32_e32 v58, v59, v58, vcc
	v_div_scale_f32 v59, s[0:1], v58, v58, 1.0
	v_rcp_f32_e32 v68, v59
	v_div_scale_f32 v69, vcc, 1.0, v58, 1.0
	v_fma_f32 v102, -v59, v68, 1.0
	v_fmac_f32_e32 v68, v102, v68
	v_mul_f32_e32 v102, v69, v68
	v_fma_f32 v103, -v59, v102, v69
	v_fmac_f32_e32 v102, v103, v68
	v_fma_f32 v59, -v59, v102, v69
	v_div_fmas_f32 v59, v59, v68, v102
	v_div_fixup_f32 v58, v59, v58, 1.0
	v_pk_mul_f32 v[64:65], v[58:59], v[64:65] op_sel_hi:[0,1]
	v_pk_mul_f32 v[66:67], v[58:59], v[66:67] op_sel_hi:[0,1]
	v_pk_mul_f32 v[68:69], v[58:59], v[56:57] op_sel_hi:[0,1]
	v_pk_mul_f32 v[56:57], v[58:59], v[70:71] op_sel_hi:[0,1]
	v_pk_mul_f32 v[70:71], v[58:59], v[72:73] op_sel_hi:[0,1]
	v_pk_mul_f32 v[72:73], v[58:59], v[74:75] op_sel_hi:[0,1]
	v_pk_mul_f32 v[102:103], v[58:59], v[48:49] op_sel_hi:[0,1]
	v_pk_mul_f32 v[50:51], v[58:59], v[50:51] op_sel_hi:[0,1]
	v_pk_fma_f32 v[48:49], v[2:3], v[66:67], v[52:53]
	v_pk_fma_f32 v[52:53], v[0:1], v[64:65], v[76:77]
	v_pk_fma_f32 v[56:57], v[6:7], v[56:57], v[54:55]
	v_pk_fma_f32 v[58:59], v[4:5], v[68:69], v[78:79]
	v_pk_fma_f32 v[74:75], v[14:15], v[50:51], v[100:101]
	v_pk_mul_f32 v[50:51], v[48:49], v[48:49]
	v_pk_mul_f32 v[54:55], v[52:53], v[52:53]
	v_pk_mul_f32 v[66:67], v[56:57], v[56:57]
	v_pk_mul_f32 v[68:69], v[58:59], v[58:59]
	v_pk_fma_f32 v[64:65], v[10:11], v[72:73], v[82:83]
	v_pk_fma_f32 v[70:71], v[8:9], v[70:71], v[80:81]
	v_pk_mov_b32 v[80:81], v[54:55], v[50:51] op_sel:[1,0]
	v_mov_b32_e32 v55, v51
	v_pk_mov_b32 v[50:51], v[68:69], v[66:67] op_sel:[1,0]
	v_mov_b32_e32 v69, v67
	v_mul_f32_e32 v72, v70, v70
	v_mul_f32_e32 v76, v64, v64
	v_pk_add_f32 v[54:55], v[80:81], v[54:55]
	v_pk_add_f32 v[50:51], v[50:51], v[68:69]
	v_pk_fma_f32 v[78:79], v[12:13], v[102:103], v[98:99]
	v_pk_fma_f32 v[66:67], v[70:71], v[70:71], v[72:73] op_sel_hi:[1,1,0]
	v_pk_fma_f32 v[72:73], v[64:65], v[64:65], v[76:77] op_sel_hi:[1,1,0]
	v_pk_add_f32 v[54:55], v[54:55], v[54:55] op_sel_hi:[0,1]
	v_pk_add_f32 v[50:51], v[50:51], v[50:51] op_sel_hi:[0,1]
	v_mul_f32_e32 v66, v78, v78
	v_mul_f32_e32 v72, v79, v79
	v_mul_f32_e32 v54, v74, v74
	v_mul_f32_e32 v50, v75, v75
	v_pk_add_f32 v[66:67], v[66:67], v[72:73]
	v_pk_add_f32 v[50:51], v[54:55], v[50:51]
	v_lshlrev_b32_e32 v82, 16, v60
	v_pk_add_f32 v[50:51], v[66:67], v[50:51]
	v_and_b32_e32 v83, 0xffff0000, v60
	v_add_f32_e32 v50, v50, v51
	s_nop 1
	v_lshlrev_b32_e32 v80, 16, v61
	v_and_b32_e32 v81, 0xffff0000, v61
	v_lshlrev_b32_e32 v66, 16, v92
	v_and_b32_e32 v67, 0xffff0000, v92
	s_waitcnt lgkmcnt(0)
	v_add_f32_dpp v50, v50, v50 quad_perm:[1,0,3,2] row_mask:0xf bank_mask:0xf
	s_nop 1
	v_lshlrev_b32_e32 v76, 16, v62
	v_and_b32_e32 v77, 0xffff0000, v62
	v_lshlrev_b32_e32 v72, 16, v63
	v_and_b32_e32 v73, 0xffff0000, v63
	s_waitcnt lgkmcnt(0)
	v_add_f32_dpp v50, v50, v50 quad_perm:[2,3,0,1] row_mask:0xf bank_mask:0xf
	s_nop 1
	v_lshlrev_b32_e32 v62, 16, v93
	v_and_b32_e32 v63, 0xffff0000, v93
	v_lshlrev_b32_e32 v68, 16, v35
	v_and_b32_e32 v69, 0xffff0000, v35
	s_waitcnt lgkmcnt(0)
	v_add_f32_dpp v60, v50, v50 row_half_mirror row_mask:0xf bank_mask:0xf
	s_nop 1
	v_lshlrev_b32_e32 v54, 16, v94
	v_and_b32_e32 v55, 0xffff0000, v94
	v_lshlrev_b32_e32 v50, 16, v95
	v_and_b32_e32 v51, 0xffff0000, v95
	s_waitcnt lgkmcnt(0)
	v_add_f32_dpp v92, v60, v60 row_mirror row_mask:0xf bank_mask:0xf
	ds_bpermute_b32 v93, v88, v92
	v_lshlrev_b32_e32 v60, 16, v34
	v_and_b32_e32 v61, 0xffff0000, v34
	v_lshlrev_b32_e32 v100, 16, v32
	v_and_b32_e32 v101, 0xffff0000, v32
	s_waitcnt lgkmcnt(0)
	v_add_f32_e32 v34, v92, v93
	ds_bpermute_b32 v35, v89, v34
	v_cvt_pk_bf16_f32 v92, v52, v53
	v_cvt_pk_bf16_f32 v93, v48, v49
	v_cvt_pk_bf16_f32 v94, v58, v59
	v_cvt_pk_bf16_f32 v95, v56, v57
	s_waitcnt lgkmcnt(0)
	v_add_f32_e32 v34, v34, v35
	v_fmamk_f32 v34, v34, 0x3a800000, v90
	v_mul_f32_e32 v35, 0x4f800000, v34
	v_cmp_gt_f32_e32 vcc, s8, v34
	global_store_dwordx4 v[96:97], v[92:95], off
	v_mul_f32_e32 v32, v100, v100
	v_cndmask_b32_e32 v34, v34, v35, vcc
	v_sqrt_f32_e32 v35, v34
	v_cvt_pk_bf16_f32 v92, v70, v71
	v_cvt_pk_bf16_f32 v93, v64, v65
	v_pk_fma_f32 v[102:103], v[100:101], v[100:101], v[32:33] op_sel_hi:[1,1,0]
	v_add_u32_e32 v94, -1, v35
	v_add_u32_e32 v95, 1, v35
	v_fma_f32 v98, -v94, v35, v34
	v_fma_f32 v99, -v95, v35, v34
	v_cmp_ge_f32_e64 s[0:1], 0, v98
	v_mul_f32_e32 v32, v104, v104
	v_pk_fma_f32 v[32:33], v[104:105], v[104:105], v[32:33] op_sel_hi:[1,1,0]
	v_cndmask_b32_e64 v35, v35, v94, s[0:1]
	v_cmp_lt_f32_e64 s[0:1], 0, v99
	v_mul_f32_e32 v102, v68, v68
	v_mul_f32_e32 v32, v69, v69
	v_cndmask_b32_e64 v35, v35, v95, s[0:1]
	v_mul_f32_e32 v94, 0x37800000, v35
	v_cndmask_b32_e32 v35, v35, v94, vcc
	v_cmp_class_f32_e32 vcc, v34, v91
	v_cvt_pk_bf16_f32 v94, v78, v79
	v_cvt_pk_bf16_f32 v95, v74, v75
	global_store_dwordx4 v[96:97], v[92:95], off offset:1024
	v_lshlrev_b32_e32 v97, 16, v39
	v_cndmask_b32_e32 v108, v35, v34, vcc
	v_div_scale_f32 v34, s[0:1], v108, v108, 1.0
	v_rcp_f32_e32 v109, v34
	v_and_b32_e32 v93, 0xffff0000, v36
	v_lshlrev_b32_e32 v96, 16, v38
	v_and_b32_e32 v39, 0xffff0000, v39
	v_fma_f32 v35, -v34, v109, 1.0
	v_fmac_f32_e32 v109, v35, v109
	v_div_scale_f32 v35, vcc, 1.0, v108, 1.0
	v_mul_f32_e32 v110, v35, v109
	v_fma_f32 v92, -v34, v110, v35
	v_fmac_f32_e32 v110, v92, v109
	v_lshlrev_b32_e32 v92, 16, v36
	v_lshlrev_b32_e32 v36, 16, v37
	v_and_b32_e32 v38, 0xffff0000, v38
	v_fma_f32 v111, -v34, v110, v35
	v_mul_f32_e32 v34, v92, v92
	v_and_b32_e32 v37, 0xffff0000, v37
	v_mul_f32_e32 v94, v36, v36
	v_pk_mul_f32 v[98:99], v[38:39], v[38:39]
	v_pk_fma_f32 v[34:35], v[92:93], v[92:93], v[34:35] op_sel_hi:[1,1,0]
	v_pk_fma_f32 v[94:95], v[36:37], v[36:37], v[94:95] op_sel_hi:[1,1,0]
	v_pk_fma_f32 v[98:99], v[96:97], v[96:97], v[98:99]
	v_pk_add_f32 v[34:35], v[34:35], v[94:95]
	v_pk_add_f32 v[98:99], v[98:99], v[98:99] op_sel_hi:[0,1]
	v_mul_f32_e32 v98, v61, v61
	v_mul_f32_e32 v106, v60, v60
	v_mov_b32_e32 v107, v35
	v_pk_add_f32 v[34:35], v[106:107], v[98:99]
	v_pk_add_f32 v[32:33], v[102:103], v[32:33]
	s_nop 0
	v_pk_add_f32 v[32:33], v[34:35], v[32:33]
	s_nop 0
	v_add_f32_e32 v33, v32, v33
	s_nop 1
	v_div_fmas_f32 v32, v111, v109, v110
	v_div_fixup_f32 v32, v32, v108, 1.0
	v_pk_mul_f32 v[34:35], v[78:79], v[32:33] op_sel_hi:[1,0]
	s_waitcnt lgkmcnt(0)
	v_add_f32_dpp v33, v33, v33 quad_perm:[1,0,3,2] row_mask:0xf bank_mask:0xf
	s_nop 1
	v_pk_mul_f32 v[74:75], v[74:75], v[32:33] op_sel_hi:[1,0]
	v_pk_mul_f32 v[78:79], v[28:29], v[34:35]
	v_pk_mul_f32 v[34:35], v[70:71], v[32:33] op_sel_hi:[1,0]
	v_pk_mul_f32 v[74:75], v[30:31], v[74:75]
	s_waitcnt lgkmcnt(0)
	v_add_f32_dpp v33, v33, v33 quad_perm:[2,3,0,1] row_mask:0xf bank_mask:0xf
	s_nop 1
	v_pk_mul_f32 v[64:65], v[64:65], v[32:33] op_sel_hi:[1,0]
	v_pk_mul_f32 v[70:71], v[24:25], v[34:35]
	v_pk_mul_f32 v[34:35], v[58:59], v[32:33] op_sel_hi:[1,0]
	v_pk_mul_f32 v[64:65], v[26:27], v[64:65]
	s_waitcnt lgkmcnt(0)
	v_add_f32_dpp v33, v33, v33 row_half_mirror row_mask:0xf bank_mask:0xf
	s_nop 1
	v_pk_mul_f32 v[56:57], v[56:57], v[32:33] op_sel_hi:[1,0]
	v_pk_mul_f32 v[52:53], v[52:53], v[32:33] op_sel_hi:[1,0]
	v_pk_mul_f32 v[34:35], v[20:21], v[34:35]
	v_pk_mul_f32 v[56:57], v[22:23], v[56:57]
	s_waitcnt lgkmcnt(0)
	v_add_f32_dpp v58, v33, v33 row_mirror row_mask:0xf bank_mask:0xf
	ds_bpermute_b32 v59, v88, v58
	v_pk_mul_f32 v[32:33], v[48:49], v[32:33] op_sel_hi:[1,0]
	s_waitcnt lgkmcnt(0)
	v_add_f32_e32 v58, v58, v59
	ds_bpermute_b32 v59, v89, v58
	v_pk_mul_f32 v[48:49], v[18:19], v[32:33]
	v_pk_mul_f32 v[32:33], v[16:17], v[52:53]
	v_lshl_add_u64 v[52:53], v[44:45], 0, s[6:7]
	v_cvt_pk_bf16_f32 v32, v32, v33
	v_cvt_pk_bf16_f32 v33, v48, v49
	s_waitcnt lgkmcnt(0)
	v_add_f32_e32 v48, v58, v59
	v_fmamk_f32 v48, v48, 0x3a800000, v90
	v_mul_f32_e32 v49, 0x4f800000, v48
	v_cmp_gt_f32_e32 vcc, s8, v48
	v_cvt_pk_bf16_f32 v34, v34, v35
	v_cvt_pk_bf16_f32 v35, v56, v57
	global_store_dwordx4 v[52:53], v[32:35], off
	s_mov_b64 s[6:7], -1
	v_cndmask_b32_e32 v48, v48, v49, vcc
	v_sqrt_f32_e32 v49, v48
	v_cvt_pk_bf16_f32 v32, v70, v71
	v_cvt_pk_bf16_f32 v33, v64, v65
	s_nop 0
	v_add_u32_e32 v34, -1, v49
	v_fma_f32 v35, -v34, v49, v48
	v_cmp_ge_f32_e64 s[0:1], 0, v35
	v_add_u32_e32 v35, 1, v49
	s_nop 0
	v_cndmask_b32_e64 v34, v49, v34, s[0:1]
	v_fma_f32 v49, -v35, v49, v48
	v_cmp_lt_f32_e64 s[0:1], 0, v49
	s_nop 1
	v_cndmask_b32_e64 v34, v34, v35, s[0:1]
	v_mul_f32_e32 v35, 0x37800000, v34
	v_cndmask_b32_e32 v34, v34, v35, vcc
	v_cmp_class_f32_e32 vcc, v48, v91
	s_nop 1
	v_cndmask_b32_e32 v48, v34, v48, vcc
	v_div_scale_f32 v49, s[0:1], v48, v48, 1.0
	v_rcp_f32_e32 v56, v49
	v_cvt_pk_bf16_f32 v34, v78, v79
	v_cvt_pk_bf16_f32 v35, v74, v75
	global_store_dwordx4 v[52:53], v[32:35], off offset:1024
	s_cselect_b64 s[0:1], -1, 0
	s_nop 0
	v_fma_f32 v32, -v49, v56, 1.0
	v_fmac_f32_e32 v56, v32, v56
	v_div_scale_f32 v32, vcc, 1.0, v48, 1.0
	v_mul_f32_e32 v33, v32, v56
	v_fma_f32 v34, -v49, v33, v32
	v_fmac_f32_e32 v33, v34, v56
	v_fma_f32 v32, -v49, v33, v32
	v_div_fmas_f32 v32, v32, v56, v33
	v_div_fixup_f32 v56, v32, v48, 1.0
	v_pk_mul_f32 v[32:33], v[56:57], v[36:37] op_sel_hi:[0,1]
	v_mov_b32_e32 v36, v97
	v_mov_b32_e32 v37, v39
	v_mov_b32_e32 v97, v38
	v_pk_mul_f32 v[34:35], v[56:57], v[92:93] op_sel_hi:[0,1]
	v_pk_mul_f32 v[36:37], v[56:57], v[36:37] op_sel_hi:[0,1]
	v_pk_mul_f32 v[38:39], v[56:57], v[96:97] op_sel_hi:[0,1]
	v_pk_mul_f32 v[48:49], v[56:57], v[104:105] op_sel_hi:[0,1]
	v_pk_mul_f32 v[52:53], v[56:57], v[100:101] op_sel_hi:[0,1]
	v_pk_mul_f32 v[58:59], v[56:57], v[68:69] op_sel_hi:[0,1]
	v_pk_mul_f32 v[56:57], v[56:57], v[60:61] op_sel_hi:[0,1]
	v_pk_fma_f32 v[34:35], v[0:1], v[34:35], v[82:83]
	v_pk_fma_f32 v[32:33], v[2:3], v[32:33], v[80:81]
	v_pk_fma_f32 v[38:39], v[4:5], v[38:39], v[76:77]
	v_pk_fma_f32 v[36:37], v[6:7], v[36:37], v[72:73]
	v_pk_fma_f32 v[52:53], v[8:9], v[52:53], v[66:67]
	v_pk_fma_f32 v[48:49], v[10:11], v[48:49], v[62:63]
	v_pk_fma_f32 v[54:55], v[12:13], v[56:57], v[54:55]
	v_pk_fma_f32 v[50:51], v[14:15], v[58:59], v[50:51]
	s_and_b64 vcc, exec, s[0:1]
	s_cbranch_vccnz .LBB0_1341
	s_mov_b64 s[6:7], 0

.LBB0_1343:
	s_nop 1
	v_mul_f32_e32 v56, v34, v34
	v_mul_f32_e32 v57, v32, v32
	v_fmac_f32_e32 v56, v35, v35
	v_fmac_f32_e32 v57, v33, v33
	v_add_f32_e32 v56, v57, v56
	v_mul_f32_e32 v57, v38, v38
	v_mul_f32_e32 v58, v36, v36
	v_fmac_f32_e32 v57, v39, v39
	v_fmac_f32_e32 v58, v37, v37
	v_add_f32_e32 v57, v58, v57
	v_add_f32_e32 v56, v57, v56
	v_mul_f32_e32 v57, v52, v52
	v_mul_f32_e32 v58, v48, v48
	v_fmac_f32_e32 v57, v53, v53
	v_fmac_f32_e32 v58, v49, v49
	v_add_f32_e32 v57, v58, v57
	v_add_f32_e32 v56, v57, v56
	v_mul_f32_e32 v57, v54, v54
	v_mul_f32_e32 v58, v50, v50
	v_fmac_f32_e32 v57, v55, v55
	v_fmac_f32_e32 v58, v51, v51
	v_add_f32_e32 v57, v58, v57
	v_add_f32_e32 v56, v57, v56
	s_nop 1
	s_andn2_b64 vcc, exec, s[0:1]
	s_waitcnt lgkmcnt(0)
	v_add_f32_dpp v56, v56, v56 quad_perm:[1,0,3,2] row_mask:0xf bank_mask:0xf
	s_nop 1
	s_waitcnt lgkmcnt(0)
	v_add_f32_dpp v56, v56, v56 quad_perm:[2,3,0,1] row_mask:0xf bank_mask:0xf
	s_nop 1
	s_waitcnt lgkmcnt(0)
	v_add_f32_dpp v56, v56, v56 row_half_mirror row_mask:0xf bank_mask:0xf
	s_nop 1
	s_waitcnt lgkmcnt(0)
	v_add_f32_dpp v56, v56, v56 row_mirror row_mask:0xf bank_mask:0xf
	ds_bpermute_b32 v57, v88, v56
	s_waitcnt lgkmcnt(0)
	v_add_f32_e32 v56, v56, v57
	ds_bpermute_b32 v57, v89, v56
	s_cbranch_vccnz .LBB0_1338
	s_waitcnt lgkmcnt(0)
	v_add_f32_e32 v56, v56, v57
	v_fmamk_f32 v56, v56, 0x3a800000, v90
	v_mul_f32_e32 v57, 0x4f800000, v56
	v_cmp_gt_f32_e32 vcc, s8, v56
	s_ashr_i32 s5, s4, 31
	s_nop 0
	v_cndmask_b32_e32 v56, v56, v57, vcc
	v_sqrt_f32_e32 v57, v56
	s_nop 0
	v_add_u32_e32 v58, -1, v57
	v_fma_f32 v60, -v58, v57, v56
	v_add_u32_e32 v59, 1, v57
	v_cmp_ge_f32_e64 s[0:1], 0, v60
	s_nop 1
	v_cndmask_b32_e64 v58, v57, v58, s[0:1]
	v_fma_f32 v57, -v59, v57, v56
	v_cmp_lt_f32_e64 s[0:1], 0, v57
	s_nop 1
	v_cndmask_b32_e64 v57, v58, v59, s[0:1]
	v_mul_f32_e32 v58, 0x37800000, v57
	v_cndmask_b32_e32 v57, v57, v58, vcc
	v_cmp_class_f32_e32 vcc, v56, v91
	s_nop 1
	v_cndmask_b32_e32 v56, v57, v56, vcc
	v_div_scale_f32 v57, s[0:1], v56, v56, 1.0
	v_rcp_f32_e32 v58, v57
	s_lshl_b64 s[0:1], s[4:5], 11
	v_fma_f32 v59, -v57, v58, 1.0
	v_fmac_f32_e32 v58, v59, v58
	v_div_scale_f32 v59, vcc, 1.0, v56, 1.0
	v_mul_f32_e32 v60, v59, v58
	v_fma_f32 v61, -v57, v60, v59
	v_fmac_f32_e32 v60, v61, v58
	v_fma_f32 v57, -v57, v60, v59
	v_div_fmas_f32 v57, v57, v58, v60
	v_div_fixup_f32 v56, v57, v56, 1.0
	v_pk_mul_f32 v[34:35], v[34:35], v[56:57] op_sel_hi:[1,0]
	v_pk_mul_f32 v[32:33], v[32:33], v[56:57] op_sel_hi:[1,0]
	v_pk_mul_f32 v[54:55], v[54:55], v[56:57] op_sel_hi:[1,0]
	v_pk_mul_f32 v[50:51], v[50:51], v[56:57] op_sel_hi:[1,0]
	v_pk_mul_f32 v[52:53], v[52:53], v[56:57] op_sel_hi:[1,0]
	v_pk_mul_f32 v[48:49], v[48:49], v[56:57] op_sel_hi:[1,0]
	v_pk_mul_f32 v[38:39], v[38:39], v[56:57] op_sel_hi:[1,0]
	v_pk_mul_f32 v[36:37], v[36:37], v[56:57] op_sel_hi:[1,0]
	v_pk_mul_f32 v[56:57], v[18:19], v[32:33]
	v_pk_mul_f32 v[32:33], v[16:17], v[34:35]
	v_pk_mul_f32 v[36:37], v[22:23], v[36:37]
	v_pk_mul_f32 v[38:39], v[20:21], v[38:39]
	v_lshl_add_u64 v[58:59], v[44:45], 0, s[0:1]
	v_cvt_pk_bf16_f32 v32, v32, v33
	v_cvt_pk_bf16_f32 v33, v56, v57
	v_cvt_pk_bf16_f32 v34, v38, v39
	v_cvt_pk_bf16_f32 v35, v36, v37
	v_pk_mul_f32 v[50:51], v[30:31], v[50:51]
	v_pk_mul_f32 v[54:55], v[28:29], v[54:55]
	v_pk_mul_f32 v[48:49], v[26:27], v[48:49]
	v_pk_mul_f32 v[52:53], v[24:25], v[52:53]
	global_store_dwordx4 v[58:59], v[32:35], off
	s_nop 1
	v_cvt_pk_bf16_f32 v32, v52, v53
	v_cvt_pk_bf16_f32 v33, v48, v49
	v_cvt_pk_bf16_f32 v34, v54, v55
	v_cvt_pk_bf16_f32 v35, v50, v51
	global_store_dwordx4 v[58:59], v[32:35], off offset:1024
	s_branch .LBB0_1338

.LBB0_1553:
	s_ashr_i32 s5, s4, 31
	s_lshl_b64 s[0:1], s[4:5], 11
	v_lshl_add_u64 v[36:37], v[40:41], 0, s[0:1]
	global_load_dwordx4 v[32:35], v[36:37], off
	global_load_dwordx4 v[46:49], v[36:37], off offset:1024
	v_lshl_add_u64 v[36:37], v[42:43], 0, s[0:1]
	s_add_i32 s6, s4, s83
	s_waitcnt lgkmcnt(0)
	global_load_dwordx4 v[50:53], v[36:37], off
	global_load_dwordx4 v[54:57], v[36:37], off offset:1024
	s_min_i32 s0, s6, 0xffff
	s_ashr_i32 s1, s0, 31
	s_lshl_b64 s[0:1], s[0:1], 11
	v_lshl_add_u64 v[58:59], v[42:43], 0, s[0:1]
	global_load_dwordx4 v[36:39], v[58:59], off
	s_waitcnt vmcnt(0)
	v_and_b32_e32 v61, 0xffff0000, v32
	v_and_b32_e32 v63, 0xffff0000, v33
	v_and_b32_e32 v65, 0xffff0000, v34
	v_and_b32_e32 v83, 0xffff0000, v35
	v_lshlrev_b32_e32 v60, 16, v32
	v_lshlrev_b32_e32 v62, 16, v33
	v_lshlrev_b32_e32 v64, 16, v34
	v_lshlrev_b32_e32 v82, 16, v35
	v_and_b32_e32 v85, 0xffff0000, v46
	v_and_b32_e32 v87, 0xffff0000, v47
	v_mul_f32_e32 v32, v61, v61
	v_mul_f32_e32 v33, v63, v63
	v_mul_f32_e32 v34, v65, v65
	v_mul_f32_e32 v35, v83, v83
	v_lshlrev_b32_e32 v84, 16, v46
	v_lshlrev_b32_e32 v86, 16, v47
	v_and_b32_e32 v89, 0xffff0000, v48
	v_and_b32_e32 v91, 0xffff0000, v49
	v_mul_f32_e32 v46, v85, v85
	v_mul_f32_e32 v47, v87, v87
	v_fmac_f32_e32 v32, v60, v60
	v_fmac_f32_e32 v33, v62, v62
	v_fmac_f32_e32 v34, v64, v64
	v_fmac_f32_e32 v35, v82, v82
	v_lshlrev_b32_e32 v88, 16, v48
	v_lshlrev_b32_e32 v90, 16, v49
	v_mul_f32_e32 v48, v89, v89
	v_mul_f32_e32 v49, v91, v91
	v_fmac_f32_e32 v46, v84, v84
	v_fmac_f32_e32 v47, v86, v86
	v_add_f32_e32 v32, v32, v33
	v_add_f32_e32 v33, v34, v35
	v_fmac_f32_e32 v48, v88, v88
	v_fmac_f32_e32 v49, v90, v90
	v_add_f32_e32 v34, v46, v47
	v_add_f32_e32 v32, v32, v33
	v_add_f32_e32 v35, v48, v49
	v_add_f32_e32 v32, v32, v34
	v_add_f32_e32 v48, v35, v32
	s_nop 1
	global_load_dwordx4 v[32:35], v[58:59], off offset:1024
	v_lshl_add_u64 v[46:47], v[40:41], 0, s[0:1]
	global_load_dwordx4 v[66:69], v[46:47], off
	global_load_dwordx4 v[78:81], v[46:47], off offset:1024
	v_lshlrev_b32_e32 v58, 16, v50
	s_waitcnt lgkmcnt(0)
	v_add_f32_dpp v48, v48, v48 quad_perm:[1,0,3,2] row_mask:0xf bank_mask:0xf
	s_nop 1
	v_and_b32_e32 v59, 0xffff0000, v50
	v_lshlrev_b32_e32 v92, 16, v51
	v_and_b32_e32 v93, 0xffff0000, v51
	v_lshlrev_b32_e32 v94, 16, v52
	s_waitcnt lgkmcnt(0)
	v_add_f32_dpp v46, v48, v48 quad_perm:[2,3,0,1] row_mask:0xf bank_mask:0xf
	s_nop 1
	v_lshlrev_b32_e32 v48, 16, v37
	v_and_b32_e32 v95, 0xffff0000, v52
	v_lshlrev_b32_e32 v96, 16, v53
	v_and_b32_e32 v97, 0xffff0000, v53
	s_waitcnt lgkmcnt(0)
	v_add_f32_dpp v46, v46, v46 row_half_mirror row_mask:0xf bank_mask:0xf
	s_nop 1
	v_lshlrev_b32_e32 v98, 16, v54
	v_and_b32_e32 v99, 0xffff0000, v54
	v_lshlrev_b32_e32 v100, 16, v55
	v_and_b32_e32 v101, 0xffff0000, v55
	s_waitcnt lgkmcnt(0)
	v_add_f32_dpp v46, v46, v46 row_mirror row_mask:0xf bank_mask:0xf
	ds_bpermute_b32 v47, v74, v46
	v_lshlrev_b32_e32 v102, 16, v56
	v_and_b32_e32 v103, 0xffff0000, v56
	v_lshlrev_b32_e32 v104, 16, v57
	v_and_b32_e32 v105, 0xffff0000, v57
	s_waitcnt lgkmcnt(0)
	v_add_f32_e32 v49, v46, v47
	ds_bpermute_b32 v50, v75, v49
	v_lshlrev_b32_e32 v46, 16, v36
	v_and_b32_e32 v47, 0xffff0000, v36
	s_waitcnt lgkmcnt(0)
	v_add_f32_e32 v36, v49, v50
	v_fmamk_f32 v36, v36, 0x3a800000, v76
	v_mul_f32_e32 v49, 0x4f800000, v36
	v_cmp_gt_f32_e32 vcc, s8, v36
	s_nop 1
	v_cndmask_b32_e32 v50, v36, v49, vcc
	v_sqrt_f32_e32 v51, v50
	v_and_b32_e32 v49, 0xffff0000, v37
	v_lshlrev_b32_e32 v36, 16, v38
	v_and_b32_e32 v37, 0xffff0000, v38
	v_add_u32_e32 v38, -1, v51
	v_add_u32_e32 v52, 1, v51
	v_fma_f32 v53, -v38, v51, v50
	v_fma_f32 v54, -v52, v51, v50
	v_cmp_ge_f32_e64 s[0:1], 0, v53
	s_nop 1
	v_cndmask_b32_e64 v38, v51, v38, s[0:1]
	v_cmp_lt_f32_e64 s[0:1], 0, v54
	s_nop 1
	v_cndmask_b32_e64 v38, v38, v52, s[0:1]
	v_mul_f32_e32 v51, 0x37800000, v38
	v_cndmask_b32_e32 v38, v38, v51, vcc
	v_cmp_class_f32_e32 vcc, v50, v77
	s_nop 1
	v_cndmask_b32_e32 v50, v38, v50, vcc
	v_div_scale_f32 v51, s[0:1], v50, v50, 1.0
	v_rcp_f32_e32 v52, v51
	v_div_scale_f32 v53, vcc, 1.0, v50, 1.0
	v_lshlrev_b32_e32 v38, 16, v39
	v_fma_f32 v54, -v51, v52, 1.0
	v_fmac_f32_e32 v52, v54, v52
	v_mul_f32_e32 v54, v53, v52
	v_fma_f32 v55, -v51, v54, v53
	v_fmac_f32_e32 v54, v55, v52
	v_fma_f32 v51, -v51, v54, v53
	v_div_fmas_f32 v51, v51, v52, v54
	v_div_fixup_f32 v50, v51, v50, 1.0
	v_mul_f32_e32 v50, 0.5, v50
	v_pk_mul_f32 v[52:53], v[50:51], v[62:63] op_sel_hi:[0,1]
	v_pk_mul_f32 v[54:55], v[50:51], v[60:61] op_sel_hi:[0,1]
	v_pk_mul_f32 v[56:57], v[50:51], v[82:83] op_sel_hi:[0,1]
	v_pk_mul_f32 v[60:61], v[50:51], v[64:65] op_sel_hi:[0,1]
	v_pk_mul_f32 v[62:63], v[50:51], v[84:85] op_sel_hi:[0,1]
	v_pk_mul_f32 v[64:65], v[50:51], v[86:87] op_sel_hi:[0,1]
	v_pk_mul_f32 v[82:83], v[50:51], v[88:89] op_sel_hi:[0,1]
	v_pk_mul_f32 v[84:85], v[50:51], v[90:91] op_sel_hi:[0,1]
	v_pk_fma_f32 v[50:51], v[0:1], v[54:55], v[58:59]
	v_pk_fma_f32 v[52:53], v[2:3], v[52:53], v[92:93]
	v_pk_fma_f32 v[54:55], v[4:5], v[60:61], v[94:95]
	v_pk_fma_f32 v[56:57], v[6:7], v[56:57], v[96:97]
	v_pk_fma_f32 v[58:59], v[10:11], v[64:65], v[100:101]
	v_pk_fma_f32 v[60:61], v[8:9], v[62:63], v[98:99]
	v_pk_fma_f32 v[62:63], v[14:15], v[84:85], v[104:105]
	v_pk_fma_f32 v[64:65], v[12:13], v[82:83], v[102:103]
	v_pk_mul_f32 v[82:83], v[52:53], v[52:53]
	v_pk_mul_f32 v[84:85], v[50:51], v[50:51]
	v_pk_mul_f32 v[86:87], v[56:57], v[56:57]
	v_pk_mul_f32 v[88:89], v[54:55], v[54:55]
	v_pk_mov_b32 v[94:95], v[84:85], v[82:83] op_sel:[1,0]
	v_mov_b32_e32 v85, v83
	v_pk_mov_b32 v[82:83], v[88:89], v[86:87] op_sel:[1,0]
	v_mov_b32_e32 v89, v87
	v_mul_f32_e32 v90, v60, v60
	v_mul_f32_e32 v92, v58, v58
	v_pk_add_f32 v[84:85], v[94:95], v[84:85]
	v_pk_add_f32 v[82:83], v[82:83], v[88:89]
	v_pk_fma_f32 v[86:87], v[60:61], v[60:61], v[90:91] op_sel_hi:[1,1,0]
	v_pk_fma_f32 v[90:91], v[58:59], v[58:59], v[92:93] op_sel_hi:[1,1,0]
	v_pk_add_f32 v[84:85], v[84:85], v[84:85] op_sel_hi:[0,1]
	v_pk_add_f32 v[82:83], v[82:83], v[82:83] op_sel_hi:[0,1]
	v_mul_f32_e32 v86, v64, v64
	v_mul_f32_e32 v90, v65, v65
	v_mul_f32_e32 v84, v62, v62
	v_mul_f32_e32 v82, v63, v63
	v_pk_add_f32 v[86:87], v[86:87], v[90:91]
	v_pk_add_f32 v[82:83], v[84:85], v[82:83]
	s_waitcnt vmcnt(2)
	v_lshlrev_b32_e32 v84, 16, v33
	v_pk_add_f32 v[82:83], v[86:87], v[82:83]
	s_waitcnt vmcnt(0)
	v_lshlrev_b32_e32 v90, 16, v78
	v_add_f32_e32 v85, v82, v83
	s_nop 1
	v_lshlrev_b32_e32 v82, 16, v32
	v_and_b32_e32 v83, 0xffff0000, v32
	v_lshlrev_b32_e32 v32, 16, v34
	v_lshlrev_b32_e32 v92, 16, v80
	s_waitcnt lgkmcnt(0)
	v_add_f32_dpp v87, v85, v85 quad_perm:[1,0,3,2] row_mask:0xf bank_mask:0xf
	s_nop 1
	v_and_b32_e32 v85, 0xffff0000, v33
	v_and_b32_e32 v33, 0xffff0000, v34
	v_lshlrev_b32_e32 v86, 16, v66
	v_and_b32_e32 v39, 0xffff0000, v39
	s_waitcnt lgkmcnt(0)
	v_add_f32_dpp v34, v87, v87 quad_perm:[2,3,0,1] row_mask:0xf bank_mask:0xf
	s_nop 1
	v_and_b32_e32 v87, 0xffff0000, v66
	v_lshlrev_b32_e32 v66, 16, v67
	v_and_b32_e32 v67, 0xffff0000, v67
	v_mul_f32_e32 v95, v87, v87
	s_waitcnt lgkmcnt(0)
	v_add_f32_dpp v34, v34, v34 row_half_mirror row_mask:0xf bank_mask:0xf
	s_nop 1
	v_mul_f32_e32 v96, v67, v67
	v_lshlrev_b32_e32 v88, 16, v68
	v_and_b32_e32 v89, 0xffff0000, v68
	v_lshlrev_b32_e32 v68, 16, v69
	v_and_b32_e32 v69, 0xffff0000, v69
	s_waitcnt lgkmcnt(0)
	v_add_f32_dpp v34, v34, v34 row_mirror row_mask:0xf bank_mask:0xf
	v_fmac_f32_e32 v95, v86, v86
	v_fmac_f32_e32 v96, v66, v66
	ds_bpermute_b32 v93, v74, v34
	v_add_f32_e32 v95, v95, v96
	v_mul_f32_e32 v96, v89, v89
	v_mul_f32_e32 v97, v69, v69
	v_fmac_f32_e32 v96, v88, v88
	v_fmac_f32_e32 v97, v68, v68
	v_and_b32_e32 v91, 0xffff0000, v78
	v_lshlrev_b32_e32 v78, 16, v79
	v_and_b32_e32 v79, 0xffff0000, v79
	v_add_f32_e32 v96, v96, v97
	v_add_f32_e32 v95, v95, v96
	v_mul_f32_e32 v96, v91, v91
	v_mul_f32_e32 v97, v79, v79
	v_fmac_f32_e32 v96, v90, v90
	v_fmac_f32_e32 v97, v78, v78
	s_waitcnt lgkmcnt(0)
	v_add_f32_e32 v34, v34, v93
	v_and_b32_e32 v93, 0xffff0000, v80
	v_lshlrev_b32_e32 v80, 16, v81
	v_and_b32_e32 v81, 0xffff0000, v81
	v_add_f32_e32 v96, v96, v97
	v_add_f32_e32 v95, v95, v96
	v_mul_f32_e32 v96, v93, v93
	v_mul_f32_e32 v97, v81, v81
	v_fmac_f32_e32 v96, v92, v92
	v_fmac_f32_e32 v97, v80, v80
	v_add_f32_e32 v96, v96, v97
	v_add_f32_e32 v95, v96, v95
	s_nop 1
	ds_bpermute_b32 v94, v75, v34
	s_waitcnt lgkmcnt(1)
	v_add_f32_dpp v95, v95, v95 quad_perm:[1,0,3,2] row_mask:0xf bank_mask:0xf
	s_nop 1
	s_waitcnt lgkmcnt(0)
	v_add_f32_e32 v34, v34, v94
	v_fmamk_f32 v34, v34, 0x3a800000, v76
	v_mul_f32_e32 v94, 0x4f800000, v34
	v_cmp_gt_f32_e32 vcc, s8, v34
	s_waitcnt lgkmcnt(0)
	v_add_f32_dpp v95, v95, v95 quad_perm:[2,3,0,1] row_mask:0xf bank_mask:0xf
	s_nop 1
	v_cndmask_b32_e32 v34, v34, v94, vcc
	v_sqrt_f32_e32 v97, v34
	v_lshlrev_b32_e32 v94, 16, v35
	s_waitcnt lgkmcnt(0)
	v_add_f32_dpp v95, v95, v95 row_half_mirror row_mask:0xf bank_mask:0xf
	v_add_u32_e32 v98, -1, v97
	v_fma_f32 v99, -v98, v97, v34
	v_cmp_ge_f32_e64 s[0:1], 0, v99
	v_add_u32_e32 v99, 1, v97
	s_nop 1
	v_cndmask_b32_e64 v98, v97, v98, s[0:1]
	v_fma_f32 v97, -v99, v97, v34
	v_cmp_lt_f32_e64 s[0:1], 0, v97
	s_nop 1
	v_cndmask_b32_e64 v97, v98, v99, s[0:1]
	v_mul_f32_e32 v98, 0x37800000, v97
	v_cndmask_b32_e32 v97, v97, v98, vcc
	v_cmp_class_f32_e32 vcc, v34, v77
	s_nop 1
	v_cndmask_b32_e32 v97, v97, v34, vcc
	s_waitcnt lgkmcnt(0)
	v_add_f32_dpp v34, v95, v95 row_mirror row_mask:0xf bank_mask:0xf
	ds_bpermute_b32 v96, v74, v34
	v_and_b32_e32 v95, 0xffff0000, v35
	v_div_scale_f32 v98, s[0:1], v97, v97, 1.0
	v_rcp_f32_e32 v99, v98
	s_waitcnt lgkmcnt(0)
	v_add_f32_e32 v34, v34, v96
	ds_bpermute_b32 v35, v75, v34
	v_fma_f32 v96, -v98, v99, 1.0
	v_fmac_f32_e32 v99, v96, v99
	v_div_scale_f32 v96, vcc, 1.0, v97, 1.0
	s_waitcnt lgkmcnt(0)
	v_add_f32_e32 v34, v34, v35
	v_fmamk_f32 v34, v34, 0x3a800000, v76
	v_mul_f32_e32 v35, 0x4f800000, v34
	v_cmp_gt_f32_e64 s[0:1], s8, v34
	v_mul_f32_e32 v100, v96, v99
	v_fma_f32 v101, -v98, v100, v96
	v_cndmask_b32_e64 v34, v34, v35, s[0:1]
	v_sqrt_f32_e32 v35, v34
	v_fmac_f32_e32 v100, v101, v99
	v_fma_f32 v96, -v98, v100, v96
	v_div_fmas_f32 v98, v96, v99, v100
	v_add_u32_e32 v101, -1, v35
	v_fma_f32 v102, -v101, v35, v34
	v_cmp_ge_f32_e64 s[2:3], 0, v102
	v_add_u32_e32 v102, 1, v35
	s_nop 0
	v_cndmask_b32_e64 v101, v35, v101, s[2:3]
	v_fma_f32 v35, -v102, v35, v34
	v_cmp_lt_f32_e64 s[2:3], 0, v35
	s_nop 1
	v_cndmask_b32_e64 v35, v101, v102, s[2:3]
	v_mul_f32_e32 v101, 0x37800000, v35
	v_cndmask_b32_e64 v35, v35, v101, s[0:1]
	v_cmp_class_f32_e64 s[0:1], v34, v77
	s_nop 1
	v_cndmask_b32_e64 v34, v35, v34, s[0:1]
	v_div_scale_f32 v35, s[0:1], v34, v34, 1.0
	v_rcp_f32_e32 v101, v35
	s_lshl_b64 s[0:1], s[4:5], 12
	s_cmp_gt_i32 s6, 0xffff
	v_fma_f32 v96, -v35, v101, 1.0
	v_fmac_f32_e32 v101, v96, v101
	v_div_scale_f32 v96, vcc, 1.0, v34, 1.0
	v_mul_f32_e32 v99, v96, v101
	v_fma_f32 v100, -v35, v99, v96
	v_fmac_f32_e32 v99, v100, v101
	v_fma_f32 v35, -v35, v99, v96
	v_div_fmas_f32 v35, v35, v101, v99
	v_div_fixup_f32 v34, v35, v34, 1.0
	v_mul_f32_e32 v96, 0.5, v34
	v_pk_mul_f32 v[34:35], v[96:97], v[66:67] op_sel_hi:[0,1]
	v_pk_mul_f32 v[86:87], v[96:97], v[86:87] op_sel_hi:[0,1]
	v_pk_fma_f32 v[34:35], v[2:3], v[34:35], v[48:49]
	v_pk_mul_f32 v[48:49], v[96:97], v[88:89] op_sel_hi:[0,1]
	v_pk_fma_f32 v[46:47], v[0:1], v[86:87], v[46:47]
	v_pk_fma_f32 v[36:37], v[4:5], v[48:49], v[36:37]
	v_pk_mul_f32 v[48:49], v[96:97], v[78:79] op_sel_hi:[0,1]
	v_pk_mul_f32 v[78:79], v[96:97], v[92:93] op_sel_hi:[0,1]
	v_pk_mul_f32 v[66:67], v[96:97], v[68:69] op_sel_hi:[0,1]
	v_pk_fma_f32 v[32:33], v[12:13], v[78:79], v[32:33]
	v_mul_f32_e32 v78, v47, v47
	v_mul_f32_e32 v79, v35, v35
	v_pk_fma_f32 v[38:39], v[6:7], v[66:67], v[38:39]
	v_fmac_f32_e32 v78, v46, v46
	v_fmac_f32_e32 v79, v34, v34
	v_pk_mul_f32 v[68:69], v[96:97], v[80:81] op_sel_hi:[0,1]
	v_add_f32_e32 v78, v78, v79
	v_mul_f32_e32 v79, v37, v37
	v_mul_f32_e32 v80, v39, v39
	v_pk_mul_f32 v[66:67], v[96:97], v[90:91] op_sel_hi:[0,1]
	v_fmac_f32_e32 v79, v36, v36
	v_fmac_f32_e32 v80, v38, v38
	v_pk_fma_f32 v[48:49], v[10:11], v[48:49], v[84:85]
	v_pk_fma_f32 v[66:67], v[8:9], v[66:67], v[82:83]
	v_add_f32_e32 v79, v79, v80
	v_add_f32_e32 v78, v78, v79
	v_mul_f32_e32 v79, v67, v67
	v_mul_f32_e32 v80, v49, v49
	v_fmac_f32_e32 v79, v66, v66
	v_fmac_f32_e32 v80, v48, v48
	v_pk_fma_f32 v[68:69], v[14:15], v[68:69], v[94:95]
	v_add_f32_e32 v79, v79, v80
	v_add_f32_e32 v78, v79, v78
	v_mul_f32_e32 v79, v33, v33
	v_mul_f32_e32 v80, v69, v69
	v_fmac_f32_e32 v79, v32, v32
	v_fmac_f32_e32 v80, v68, v68
	v_add_f32_e32 v79, v79, v80
	v_add_f32_e32 v79, v79, v78
	s_nop 1
	v_div_fixup_f32 v78, v98, v97, 1.0
	v_pk_mul_f32 v[80:81], v[64:65], v[78:79] op_sel_hi:[1,0]
	v_pk_mul_f32 v[62:63], v[62:63], v[78:79] op_sel_hi:[1,0]
	s_waitcnt lgkmcnt(0)
	v_add_f32_dpp v79, v79, v79 quad_perm:[1,0,3,2] row_mask:0xf bank_mask:0xf
	s_nop 1
	v_pk_mul_f32 v[64:65], v[30:31], v[62:63]
	v_pk_mul_f32 v[62:63], v[28:29], v[80:81]
	v_pk_mul_f32 v[80:81], v[60:61], v[78:79] op_sel_hi:[1,0]
	v_pk_mul_f32 v[58:59], v[58:59], v[78:79] op_sel_hi:[1,0]
	s_waitcnt lgkmcnt(0)
	v_add_f32_dpp v79, v79, v79 quad_perm:[2,3,0,1] row_mask:0xf bank_mask:0xf
	s_nop 1
	v_pk_mul_f32 v[54:55], v[54:55], v[78:79] op_sel_hi:[1,0]
	v_pk_mul_f32 v[56:57], v[56:57], v[78:79] op_sel_hi:[1,0]
	v_pk_mul_f32 v[60:61], v[26:27], v[58:59]
	v_pk_mul_f32 v[58:59], v[24:25], v[80:81]
	s_waitcnt lgkmcnt(0)
	v_add_f32_dpp v79, v79, v79 row_half_mirror row_mask:0xf bank_mask:0xf
	s_nop 1
	v_pk_mul_f32 v[50:51], v[50:51], v[78:79] op_sel_hi:[1,0]
	v_pk_mul_f32 v[52:53], v[52:53], v[78:79] op_sel_hi:[1,0]
	v_pk_mul_f32 v[50:51], v[16:17], v[50:51]
	v_pk_mul_f32 v[52:53], v[18:19], v[52:53]
	s_waitcnt lgkmcnt(0)
	v_add_f32_dpp v80, v79, v79 row_mirror row_mask:0xf bank_mask:0xf
	ds_bpermute_b32 v81, v74, v80
	v_lshl_add_u64 v[78:79], v[44:45], 0, s[0:1]
	global_store_dwordx4 v[78:79], v[50:53], off
	v_pk_mul_f32 v[56:57], v[22:23], v[56:57]
	v_pk_mul_f32 v[54:55], v[20:21], v[54:55]
	s_waitcnt lgkmcnt(0)
	v_add_f32_e32 v50, v80, v81
	ds_bpermute_b32 v51, v75, v50
	global_store_dwordx4 v[78:79], v[54:57], off offset:16
	global_store_dwordx4 v[78:79], v[58:61], off offset:2048
	global_store_dwordx4 v[78:79], v[62:65], off offset:2064
	s_cbranch_scc1 .LBB0_1552
	s_waitcnt lgkmcnt(0)
	v_add_f32_e32 v50, v50, v51
	v_fmamk_f32 v50, v50, 0x3a800000, v76
	v_mul_f32_e32 v51, 0x4f800000, v50
	v_cmp_gt_f32_e32 vcc, s8, v50
	s_ashr_i32 s7, s6, 31
	s_nop 0
	v_cndmask_b32_e32 v50, v50, v51, vcc
	v_sqrt_f32_e32 v51, v50
	s_nop 0
	v_add_u32_e32 v52, -1, v51
	v_fma_f32 v54, -v52, v51, v50
	v_add_u32_e32 v53, 1, v51
	v_cmp_ge_f32_e64 s[0:1], 0, v54
	s_nop 1
	v_cndmask_b32_e64 v52, v51, v52, s[0:1]
	v_fma_f32 v51, -v53, v51, v50
	v_cmp_lt_f32_e64 s[0:1], 0, v51
	s_nop 1
	v_cndmask_b32_e64 v51, v52, v53, s[0:1]
	v_mul_f32_e32 v52, 0x37800000, v51
	v_cndmask_b32_e32 v51, v51, v52, vcc
	v_cmp_class_f32_e32 vcc, v50, v77
	s_nop 1
	v_cndmask_b32_e32 v50, v51, v50, vcc
	v_div_scale_f32 v51, s[0:1], v50, v50, 1.0
	v_rcp_f32_e32 v52, v51
	s_lshl_b64 s[0:1], s[6:7], 12
	v_fma_f32 v53, -v51, v52, 1.0
	v_fmac_f32_e32 v52, v53, v52
	v_div_scale_f32 v53, vcc, 1.0, v50, 1.0
	v_mul_f32_e32 v54, v53, v52
	v_fma_f32 v55, -v51, v54, v53
	v_fmac_f32_e32 v54, v55, v52
	v_fma_f32 v51, -v51, v54, v53
	v_div_fmas_f32 v51, v51, v52, v54
	v_div_fixup_f32 v58, v51, v50, 1.0
	v_pk_mul_f32 v[32:33], v[32:33], v[58:59] op_sel_hi:[1,0]
	v_pk_mul_f32 v[50:51], v[68:69], v[58:59] op_sel_hi:[1,0]
	v_pk_mul_f32 v[34:35], v[34:35], v[58:59] op_sel_hi:[1,0]
	v_pk_mul_f32 v[52:53], v[30:31], v[50:51]
	v_pk_mul_f32 v[50:51], v[28:29], v[32:33]
	v_pk_mul_f32 v[32:33], v[66:67], v[58:59] op_sel_hi:[1,0]
	v_pk_mul_f32 v[48:49], v[48:49], v[58:59] op_sel_hi:[1,0]
	v_pk_mul_f32 v[54:55], v[24:25], v[32:33]
	v_pk_mul_f32 v[32:33], v[36:37], v[58:59] op_sel_hi:[1,0]
	v_pk_mul_f32 v[36:37], v[38:39], v[58:59] op_sel_hi:[1,0]
	v_pk_mul_f32 v[34:35], v[18:19], v[34:35]
	v_pk_mul_f32 v[38:39], v[22:23], v[36:37]
	v_pk_mul_f32 v[36:37], v[20:21], v[32:33]
	v_pk_mul_f32 v[32:33], v[46:47], v[58:59] op_sel_hi:[1,0]
	v_lshl_add_u64 v[46:47], v[44:45], 0, s[0:1]
	v_pk_mul_f32 v[32:33], v[16:17], v[32:33]
	v_pk_mul_f32 v[56:57], v[26:27], v[48:49]
	global_store_dwordx4 v[46:47], v[32:35], off
	global_store_dwordx4 v[46:47], v[36:39], off offset:16
	global_store_dwordx4 v[46:47], v[54:57], off offset:2048
	global_store_dwordx4 v[46:47], v[50:53], off offset:2064
	s_branch .LBB0_1552
